# A/B (7.4 step b): per-phase s_setprio 1/0 flips deleted inside the 8 GEMM K loops, on v51
# baseline (speedup 1.0000x reference)
.LBB0_248:
	s_add_u32 s6, s54, 0xfffc0080
	s_addc_u32 s20, s55, -1
	s_add_i32 s21, 0, 0x10000
	s_cmp_eq_u32 s68, 12
	s_cselect_b32 s59, s33, s20
	s_cselect_b32 s58, s39, s6
	v_add_u32_e32 v48, s21, v173
	s_cselect_b32 s57, s45, s67
	s_cselect_b32 s56, s47, s66
	s_add_i32 s6, 0, 0x14000
	ds_read_b128 v[138:141], v48
	ds_read_b128 v[142:145], v48 offset:1024
	ds_read_b128 v[146:149], v48 offset:2048
	ds_read_b128 v[150:153], v48 offset:3072
	v_add_u32_e32 v48, s6, v173
	ds_read_b128 v[156:159], v48
	ds_read_b128 v[160:163], v48 offset:1024
	ds_read_b128 v[164:167], v48 offset:2048
	ds_read_b128 v[168:171], v48 offset:3072
	v_lshl_add_u64 v[202:203], s[54:55], 0, v[134:135]
	s_add_i32 m0, s60, 0xc000
	ds_read_b128 v[178:181], v176
	ds_read_b128 v[182:185], v176 offset:1024
	ds_read_b128 v[186:189], v176 offset:2048
	ds_read_b128 v[190:193], v176 offset:3072
	ds_read_b128 v[194:197], v176 offset:4096
	ds_read_b128 v[198:201], v176 offset:5120
	ds_read_b128 v[216:219], v176 offset:6144
	ds_read_b128 v[220:223], v176 offset:7168
	global_load_lds_dwordx4 v[202:203], off
	v_lshl_add_u64 v[202:203], s[54:55], 0, v[136:137]
	s_add_i32 m0, s60, 0xe000
	s_nop 0
	global_load_lds_dwordx4 v[202:203], off
	s_waitcnt vmcnt(8)
	s_waitcnt lgkmcnt(0)
	s_barrier
	v_mfma_f32_16x16x32_bf16 v[126:129], v[138:141], v[178:181], v[126:129]
	v_mfma_f32_16x16x32_bf16 v[122:125], v[146:149], v[178:181], v[122:125]
	v_mfma_f32_16x16x32_bf16 v[110:113], v[138:141], v[186:189], v[110:113]
	v_mfma_f32_16x16x32_bf16 v[106:109], v[146:149], v[186:189], v[106:109]
	v_mfma_f32_16x16x32_bf16 v[94:97], v[138:141], v[194:197], v[94:97]
	v_mfma_f32_16x16x32_bf16 v[90:93], v[146:149], v[194:197], v[90:93]
	v_mfma_f32_16x16x32_bf16 v[78:81], v[138:141], v[216:219], v[78:81]
	v_mfma_f32_16x16x32_bf16 v[74:77], v[146:149], v[216:219], v[74:77]
	v_mfma_f32_16x16x32_bf16 v[126:129], v[142:145], v[182:185], v[126:129]
	v_mfma_f32_16x16x32_bf16 v[122:125], v[150:153], v[182:185], v[122:125]
	v_mfma_f32_16x16x32_bf16 v[110:113], v[142:145], v[190:193], v[110:113]
	v_mfma_f32_16x16x32_bf16 v[106:109], v[150:153], v[190:193], v[106:109]
	v_mfma_f32_16x16x32_bf16 v[94:97], v[142:145], v[198:201], v[94:97]
	v_mfma_f32_16x16x32_bf16 v[90:93], v[150:153], v[198:201], v[90:93]
	v_mfma_f32_16x16x32_bf16 v[78:81], v[142:145], v[220:223], v[78:81]
	v_mfma_f32_16x16x32_bf16 v[74:77], v[150:153], v[220:223], v[74:77]
	v_mfma_f32_16x16x32_bf16 v[118:121], v[156:159], v[178:181], v[118:121]
	v_mfma_f32_16x16x32_bf16 v[114:117], v[164:167], v[178:181], v[114:117]
	v_mfma_f32_16x16x32_bf16 v[102:105], v[156:159], v[186:189], v[102:105]
	v_mfma_f32_16x16x32_bf16 v[98:101], v[164:167], v[186:189], v[98:101]
	v_mfma_f32_16x16x32_bf16 v[86:89], v[156:159], v[194:197], v[86:89]
	v_mfma_f32_16x16x32_bf16 v[82:85], v[164:167], v[194:197], v[82:85]
	v_mfma_f32_16x16x32_bf16 v[70:73], v[156:159], v[216:219], v[70:73]
	v_mfma_f32_16x16x32_bf16 v[66:69], v[164:167], v[216:219], v[66:69]
	v_mfma_f32_16x16x32_bf16 v[118:121], v[160:163], v[182:185], v[118:121]
	v_mfma_f32_16x16x32_bf16 v[114:117], v[168:171], v[182:185], v[114:117]
	v_mfma_f32_16x16x32_bf16 v[102:105], v[160:163], v[190:193], v[102:105]
	v_mfma_f32_16x16x32_bf16 v[98:101], v[168:171], v[190:193], v[98:101]
	v_mfma_f32_16x16x32_bf16 v[86:89], v[160:163], v[198:201], v[86:89]
	v_mfma_f32_16x16x32_bf16 v[82:85], v[168:171], v[198:201], v[82:85]
	v_mfma_f32_16x16x32_bf16 v[70:73], v[160:163], v[220:223], v[70:73]
	v_mfma_f32_16x16x32_bf16 v[66:69], v[168:171], v[220:223], v[66:69]
	s_barrier
	s_add_i32 s20, s21, s9
	v_lshl_add_u64 v[202:203], s[56:57], 0, v[132:133]
	s_mov_b32 m0, s20
	ds_read_b128 v[178:181], v176 offset:16384
	ds_read_b128 v[182:185], v176 offset:17408
	ds_read_b128 v[186:189], v176 offset:18432
	ds_read_b128 v[190:193], v176 offset:19456
	ds_read_b128 v[194:197], v176 offset:20480
	ds_read_b128 v[198:201], v176 offset:21504
	ds_read_b128 v[216:219], v176 offset:22528
	ds_read_b128 v[220:223], v176 offset:23552
	global_load_lds_dwordx4 v[202:203], off
	s_add_i32 m0, s20, 0x2000
	s_add_u32 s20, s56, 0x40000
	v_lshl_add_u64 v[224:225], s[56:57], 0, v[130:131]
	s_addc_u32 s21, s57, 0
	s_add_i32 s6, s6, s9
	global_load_lds_dwordx4 v[224:225], off
	v_lshl_add_u64 v[226:227], s[20:21], 0, v[132:133]
	s_mov_b32 m0, s6
	v_lshl_add_u64 v[228:229], s[58:59], 0, v[130:131]
	global_load_lds_dwordx4 v[226:227], off
	v_lshl_add_u64 v[226:227], s[20:21], 0, v[130:131]
	s_add_i32 m0, s6, 0x2000
	s_nop 0
	global_load_lds_dwordx4 v[226:227], off
	v_lshl_add_u64 v[226:227], s[58:59], 0, v[132:133]
	s_mov_b32 m0, s60
	s_nop 0
	global_load_lds_dwordx4 v[226:227], off
	s_mov_b32 m0, s61
	s_nop 0
	global_load_lds_dwordx4 v[228:229], off
	s_waitcnt vmcnt(8)
	s_waitcnt lgkmcnt(0)
	s_barrier
	v_mfma_f32_16x16x32_bf16 v[62:65], v[138:141], v[178:181], v[62:65]
	v_mfma_f32_16x16x32_bf16 v[58:61], v[146:149], v[178:181], v[58:61]
	v_mfma_f32_16x16x32_bf16 v[44:47], v[138:141], v[186:189], v[44:47]
	v_mfma_f32_16x16x32_bf16 v[40:43], v[146:149], v[186:189], v[40:43]
	v_mfma_f32_16x16x32_bf16 v[28:31], v[138:141], v[194:197], v[28:31]
	v_mfma_f32_16x16x32_bf16 v[24:27], v[146:149], v[194:197], v[24:27]
	v_mfma_f32_16x16x32_bf16 v[12:15], v[138:141], v[216:219], v[12:15]
	v_mfma_f32_16x16x32_bf16 v[8:11], v[146:149], v[216:219], v[8:11]
	v_mfma_f32_16x16x32_bf16 v[62:65], v[142:145], v[182:185], v[62:65]
	v_mfma_f32_16x16x32_bf16 v[58:61], v[150:153], v[182:185], v[58:61]
	v_mfma_f32_16x16x32_bf16 v[44:47], v[142:145], v[190:193], v[44:47]
	v_mfma_f32_16x16x32_bf16 v[40:43], v[150:153], v[190:193], v[40:43]
	v_mfma_f32_16x16x32_bf16 v[28:31], v[142:145], v[198:201], v[28:31]
	v_mfma_f32_16x16x32_bf16 v[24:27], v[150:153], v[198:201], v[24:27]
	v_mfma_f32_16x16x32_bf16 v[12:15], v[142:145], v[220:223], v[12:15]
	v_mfma_f32_16x16x32_bf16 v[8:11], v[150:153], v[220:223], v[8:11]
	v_mfma_f32_16x16x32_bf16 v[54:57], v[156:159], v[178:181], v[54:57]
	v_mfma_f32_16x16x32_bf16 v[50:53], v[164:167], v[178:181], v[50:53]
	v_mfma_f32_16x16x32_bf16 v[36:39], v[156:159], v[186:189], v[36:39]
	v_mfma_f32_16x16x32_bf16 v[32:35], v[164:167], v[186:189], v[32:35]
	v_mfma_f32_16x16x32_bf16 v[20:23], v[156:159], v[194:197], v[20:23]
	v_mfma_f32_16x16x32_bf16 v[16:19], v[164:167], v[194:197], v[16:19]
	v_mfma_f32_16x16x32_bf16 v[4:7], v[156:159], v[216:219], v[4:7]
	v_mfma_f32_16x16x32_bf16 v[0:3], v[164:167], v[216:219], v[0:3]
	v_mfma_f32_16x16x32_bf16 v[54:57], v[160:163], v[182:185], v[54:57]
	v_mfma_f32_16x16x32_bf16 v[50:53], v[168:171], v[182:185], v[50:53]
	v_mfma_f32_16x16x32_bf16 v[36:39], v[160:163], v[190:193], v[36:39]
	v_mfma_f32_16x16x32_bf16 v[32:35], v[168:171], v[190:193], v[32:35]
	v_mfma_f32_16x16x32_bf16 v[20:23], v[160:163], v[198:201], v[20:23]
	v_mfma_f32_16x16x32_bf16 v[16:19], v[168:171], v[198:201], v[16:19]
	v_mfma_f32_16x16x32_bf16 v[4:7], v[160:163], v[220:223], v[4:7]
	v_mfma_f32_16x16x32_bf16 v[0:3], v[168:171], v[220:223], v[0:3]
	s_barrier
	s_add_i32 s6, 0, 0x18000
	v_add_u32_e32 v48, s6, v173
	s_add_i32 s26, 0, 0x1c000
	ds_read_b128 v[138:141], v48
	ds_read_b128 v[142:145], v48 offset:1024
	ds_read_b128 v[146:149], v48 offset:2048
	ds_read_b128 v[150:153], v48 offset:3072
	v_add_u32_e32 v48, s26, v173
	ds_read_b128 v[156:159], v48
	ds_read_b128 v[160:163], v48 offset:1024
	ds_read_b128 v[164:167], v48 offset:2048
	ds_read_b128 v[168:171], v48 offset:3072
	s_add_u32 s20, s58, 0x40000
	s_addc_u32 s21, s59, 0
	s_mov_b32 m0, s62
	v_lshl_add_u64 v[230:231], s[20:21], 0, v[132:133]
	ds_read_b128 v[178:181], v176 offset:32768
	ds_read_b128 v[182:185], v176 offset:33792
	ds_read_b128 v[186:189], v176 offset:34816
	ds_read_b128 v[190:193], v176 offset:35840
	ds_read_b128 v[194:197], v176 offset:36864
	ds_read_b128 v[198:201], v176 offset:37888
	ds_read_b128 v[216:219], v176 offset:38912
	ds_read_b128 v[220:223], v176 offset:39936
	global_load_lds_dwordx4 v[230:231], off
	v_lshl_add_u64 v[230:231], s[20:21], 0, v[130:131]
	s_mov_b32 m0, s63
	s_nop 0
	global_load_lds_dwordx4 v[230:231], off
	s_waitcnt vmcnt(8)
	s_waitcnt lgkmcnt(0)
	s_barrier
	v_mfma_f32_16x16x32_bf16 v[126:129], v[138:141], v[178:181], v[126:129]
	v_mfma_f32_16x16x32_bf16 v[122:125], v[146:149], v[178:181], v[122:125]
	v_mfma_f32_16x16x32_bf16 v[110:113], v[138:141], v[186:189], v[110:113]
	v_mfma_f32_16x16x32_bf16 v[106:109], v[146:149], v[186:189], v[106:109]
	v_mfma_f32_16x16x32_bf16 v[94:97], v[138:141], v[194:197], v[94:97]
	v_mfma_f32_16x16x32_bf16 v[90:93], v[146:149], v[194:197], v[90:93]
	v_mfma_f32_16x16x32_bf16 v[78:81], v[138:141], v[216:219], v[78:81]
	v_mfma_f32_16x16x32_bf16 v[74:77], v[146:149], v[216:219], v[74:77]
	v_mfma_f32_16x16x32_bf16 v[126:129], v[142:145], v[182:185], v[126:129]
	v_mfma_f32_16x16x32_bf16 v[122:125], v[150:153], v[182:185], v[122:125]
	v_mfma_f32_16x16x32_bf16 v[110:113], v[142:145], v[190:193], v[110:113]
	v_mfma_f32_16x16x32_bf16 v[106:109], v[150:153], v[190:193], v[106:109]
	v_mfma_f32_16x16x32_bf16 v[94:97], v[142:145], v[198:201], v[94:97]
	v_mfma_f32_16x16x32_bf16 v[90:93], v[150:153], v[198:201], v[90:93]
	v_mfma_f32_16x16x32_bf16 v[78:81], v[142:145], v[220:223], v[78:81]
	v_mfma_f32_16x16x32_bf16 v[74:77], v[150:153], v[220:223], v[74:77]
	v_mfma_f32_16x16x32_bf16 v[118:121], v[156:159], v[178:181], v[118:121]
	v_mfma_f32_16x16x32_bf16 v[114:117], v[164:167], v[178:181], v[114:117]
	v_mfma_f32_16x16x32_bf16 v[102:105], v[156:159], v[186:189], v[102:105]
	v_mfma_f32_16x16x32_bf16 v[98:101], v[164:167], v[186:189], v[98:101]
	v_mfma_f32_16x16x32_bf16 v[86:89], v[156:159], v[194:197], v[86:89]
	v_mfma_f32_16x16x32_bf16 v[82:85], v[164:167], v[194:197], v[82:85]
	v_mfma_f32_16x16x32_bf16 v[70:73], v[156:159], v[216:219], v[70:73]
	v_mfma_f32_16x16x32_bf16 v[66:69], v[164:167], v[216:219], v[66:69]
	v_mfma_f32_16x16x32_bf16 v[118:121], v[160:163], v[182:185], v[118:121]
	v_mfma_f32_16x16x32_bf16 v[114:117], v[168:171], v[182:185], v[114:117]
	v_mfma_f32_16x16x32_bf16 v[102:105], v[160:163], v[190:193], v[102:105]
	v_mfma_f32_16x16x32_bf16 v[98:101], v[168:171], v[190:193], v[98:101]
	v_mfma_f32_16x16x32_bf16 v[86:89], v[160:163], v[198:201], v[86:89]
	v_mfma_f32_16x16x32_bf16 v[82:85], v[168:171], v[198:201], v[82:85]
	v_mfma_f32_16x16x32_bf16 v[70:73], v[160:163], v[220:223], v[70:73]
	v_mfma_f32_16x16x32_bf16 v[66:69], v[168:171], v[220:223], v[66:69]
	s_barrier
	s_add_i32 s6, s6, s9
	v_lshl_add_u64 v[202:203], v[202:203], 0, s[30:31]
	s_mov_b32 m0, s6
	ds_read_b128 v[178:181], v176 offset:49152
	ds_read_b128 v[182:185], v176 offset:50176
	ds_read_b128 v[186:189], v176 offset:51200
	ds_read_b128 v[190:193], v176 offset:52224
	ds_read_b128 v[194:197], v176 offset:53248
	ds_read_b128 v[198:201], v176 offset:54272
	ds_read_b128 v[216:219], v176 offset:55296
	ds_read_b128 v[220:223], v176 offset:56320
	global_load_lds_dwordx4 v[202:203], off
	s_add_i32 m0, s6, 0x2000
	s_add_u32 s20, s56, 0x40080
	v_lshl_add_u64 v[202:203], v[224:225], 0, s[30:31]
	s_addc_u32 s21, s57, 0
	s_add_i32 s6, s26, s9
	global_load_lds_dwordx4 v[202:203], off
	v_lshl_add_u64 v[202:203], s[20:21], 0, v[132:133]
	s_mov_b32 m0, s6
	s_nop 0
	global_load_lds_dwordx4 v[202:203], off
	v_lshl_add_u64 v[202:203], s[20:21], 0, v[130:131]
	s_add_i32 m0, s6, 0x2000
	s_nop 0
	global_load_lds_dwordx4 v[202:203], off
	v_lshl_add_u64 v[202:203], v[226:227], 0, s[30:31]
	s_mov_b32 m0, s64
	s_nop 0
	global_load_lds_dwordx4 v[202:203], off
	v_lshl_add_u64 v[202:203], v[228:229], 0, s[30:31]
	s_mov_b32 m0, s65
	s_nop 0
	global_load_lds_dwordx4 v[202:203], off
	s_waitcnt vmcnt(8)
	s_waitcnt lgkmcnt(0)
	s_barrier
	v_mfma_f32_16x16x32_bf16 v[62:65], v[138:141], v[178:181], v[62:65]
	v_mfma_f32_16x16x32_bf16 v[58:61], v[146:149], v[178:181], v[58:61]
	v_mfma_f32_16x16x32_bf16 v[44:47], v[138:141], v[186:189], v[44:47]
	v_mfma_f32_16x16x32_bf16 v[40:43], v[146:149], v[186:189], v[40:43]
	v_mfma_f32_16x16x32_bf16 v[28:31], v[138:141], v[194:197], v[28:31]
	v_mfma_f32_16x16x32_bf16 v[24:27], v[146:149], v[194:197], v[24:27]
	v_mfma_f32_16x16x32_bf16 v[12:15], v[138:141], v[216:219], v[12:15]
	v_mfma_f32_16x16x32_bf16 v[8:11], v[146:149], v[216:219], v[8:11]
	v_mfma_f32_16x16x32_bf16 v[62:65], v[142:145], v[182:185], v[62:65]
	v_mfma_f32_16x16x32_bf16 v[58:61], v[150:153], v[182:185], v[58:61]
	v_mfma_f32_16x16x32_bf16 v[44:47], v[142:145], v[190:193], v[44:47]
	v_mfma_f32_16x16x32_bf16 v[40:43], v[150:153], v[190:193], v[40:43]
	v_mfma_f32_16x16x32_bf16 v[28:31], v[142:145], v[198:201], v[28:31]
	v_mfma_f32_16x16x32_bf16 v[24:27], v[150:153], v[198:201], v[24:27]
	v_mfma_f32_16x16x32_bf16 v[12:15], v[142:145], v[220:223], v[12:15]
	v_mfma_f32_16x16x32_bf16 v[8:11], v[150:153], v[220:223], v[8:11]
	v_mfma_f32_16x16x32_bf16 v[54:57], v[156:159], v[178:181], v[54:57]
	v_mfma_f32_16x16x32_bf16 v[50:53], v[164:167], v[178:181], v[50:53]
	v_mfma_f32_16x16x32_bf16 v[36:39], v[156:159], v[186:189], v[36:39]
	v_mfma_f32_16x16x32_bf16 v[32:35], v[164:167], v[186:189], v[32:35]
	v_mfma_f32_16x16x32_bf16 v[20:23], v[156:159], v[194:197], v[20:23]
	v_mfma_f32_16x16x32_bf16 v[16:19], v[164:167], v[194:197], v[16:19]
	v_mfma_f32_16x16x32_bf16 v[4:7], v[156:159], v[216:219], v[4:7]
	v_mfma_f32_16x16x32_bf16 v[0:3], v[164:167], v[216:219], v[0:3]
	v_mfma_f32_16x16x32_bf16 v[54:57], v[160:163], v[182:185], v[54:57]
	v_mfma_f32_16x16x32_bf16 v[50:53], v[168:171], v[182:185], v[50:53]
	v_mfma_f32_16x16x32_bf16 v[36:39], v[160:163], v[190:193], v[36:39]
	v_mfma_f32_16x16x32_bf16 v[32:35], v[168:171], v[190:193], v[32:35]
	v_mfma_f32_16x16x32_bf16 v[20:23], v[160:163], v[198:201], v[20:23]
	v_mfma_f32_16x16x32_bf16 v[16:19], v[168:171], v[198:201], v[16:19]
	v_mfma_f32_16x16x32_bf16 v[4:7], v[160:163], v[220:223], v[4:7]
	v_mfma_f32_16x16x32_bf16 v[0:3], v[168:171], v[220:223], v[0:3]
	s_barrier
	s_add_i32 s68, s68, 2
	s_add_u32 s54, s54, 0x100
	s_addc_u32 s55, s55, 0
	s_add_u32 s66, s66, 0x100
	s_addc_u32 s67, s67, 0
	s_cmp_gt_u32 s68, 13
	s_cbranch_scc0 .LBB0_248
	s_and_b64 vcc, exec, s[42:43]
	s_cbranch_vccz .LBB0_251
	s_barrier

.LBB0_472:
	s_add_u32 s52, s50, 0x100
	s_addc_u32 s53, s51, 0
	s_add_i32 s6, 0, 0x10000
	s_cmp_eq_u32 s71, 40
	s_cselect_b32 s57, s47, s53
	s_cselect_b32 s56, s46, s52
	v_add_u32_e32 v48, s6, v183
	s_cselect_b32 s55, s49, s70
	s_cselect_b32 s54, s48, s69
	s_add_i32 s26, 0, 0x14000
	ds_read_b128 v[122:125], v48
	ds_read_b128 v[130:133], v48 offset:1024
	ds_read_b128 v[138:141], v48 offset:2048
	ds_read_b128 v[142:145], v48 offset:3072
	v_add_u32_e32 v48, s26, v183
	ds_read_b128 v[146:149], v48
	ds_read_b128 v[150:153], v48 offset:1024
	ds_read_b128 v[168:171], v48 offset:2048
	ds_read_b128 v[172:175], v48 offset:3072
	v_lshl_add_u64 v[180:181], s[50:51], 0, v[164:165]
	s_add_i32 m0, s59, 0xc000
	ds_read_b128 v[176:179], v185
	ds_read_b128 v[186:189], v185 offset:1024
	ds_read_b128 v[190:193], v185 offset:2048
	ds_read_b128 v[194:197], v185 offset:3072
	ds_read_b128 v[198:201], v185 offset:4096
	ds_read_b128 v[216:219], v185 offset:5120
	ds_read_b128 v[220:223], v185 offset:6144
	ds_read_b128 v[224:227], v185 offset:7168
	global_load_lds_dwordx4 v[180:181], off
	v_lshl_add_u64 v[180:181], s[50:51], 0, v[166:167]
	s_add_i32 m0, s59, 0xe000
	s_nop 0
	global_load_lds_dwordx4 v[180:181], off
	s_waitcnt vmcnt(8)
	s_waitcnt lgkmcnt(0)
	s_barrier
	v_mfma_f32_16x16x32_bf16 v[134:137], v[122:125], v[176:179], v[134:137]
	v_mfma_f32_16x16x32_bf16 v[126:129], v[138:141], v[176:179], v[126:129]
	v_mfma_f32_16x16x32_bf16 v[110:113], v[122:125], v[190:193], v[110:113]
	v_mfma_f32_16x16x32_bf16 v[106:109], v[138:141], v[190:193], v[106:109]
	v_mfma_f32_16x16x32_bf16 v[94:97], v[122:125], v[198:201], v[94:97]
	v_mfma_f32_16x16x32_bf16 v[90:93], v[138:141], v[198:201], v[90:93]
	v_mfma_f32_16x16x32_bf16 v[78:81], v[122:125], v[220:223], v[78:81]
	v_mfma_f32_16x16x32_bf16 v[74:77], v[138:141], v[220:223], v[74:77]
	v_mfma_f32_16x16x32_bf16 v[134:137], v[130:133], v[186:189], v[134:137]
	v_mfma_f32_16x16x32_bf16 v[126:129], v[142:145], v[186:189], v[126:129]
	v_mfma_f32_16x16x32_bf16 v[110:113], v[130:133], v[194:197], v[110:113]
	v_mfma_f32_16x16x32_bf16 v[106:109], v[142:145], v[194:197], v[106:109]
	v_mfma_f32_16x16x32_bf16 v[94:97], v[130:133], v[216:219], v[94:97]
	v_mfma_f32_16x16x32_bf16 v[90:93], v[142:145], v[216:219], v[90:93]
	v_mfma_f32_16x16x32_bf16 v[78:81], v[130:133], v[224:227], v[78:81]
	v_mfma_f32_16x16x32_bf16 v[74:77], v[142:145], v[224:227], v[74:77]
	v_mfma_f32_16x16x32_bf16 v[118:121], v[146:149], v[176:179], v[118:121]
	v_mfma_f32_16x16x32_bf16 v[114:117], v[168:171], v[176:179], v[114:117]
	v_mfma_f32_16x16x32_bf16 v[102:105], v[146:149], v[190:193], v[102:105]
	v_mfma_f32_16x16x32_bf16 v[98:101], v[168:171], v[190:193], v[98:101]
	v_mfma_f32_16x16x32_bf16 v[86:89], v[146:149], v[198:201], v[86:89]
	v_mfma_f32_16x16x32_bf16 v[82:85], v[168:171], v[198:201], v[82:85]
	v_mfma_f32_16x16x32_bf16 v[70:73], v[146:149], v[220:223], v[70:73]
	v_mfma_f32_16x16x32_bf16 v[66:69], v[168:171], v[220:223], v[66:69]
	v_mfma_f32_16x16x32_bf16 v[118:121], v[150:153], v[186:189], v[118:121]
	v_mfma_f32_16x16x32_bf16 v[114:117], v[172:175], v[186:189], v[114:117]
	v_mfma_f32_16x16x32_bf16 v[102:105], v[150:153], v[194:197], v[102:105]
	v_mfma_f32_16x16x32_bf16 v[98:101], v[172:175], v[194:197], v[98:101]
	v_mfma_f32_16x16x32_bf16 v[86:89], v[150:153], v[216:219], v[86:89]
	v_mfma_f32_16x16x32_bf16 v[82:85], v[172:175], v[216:219], v[82:85]
	v_mfma_f32_16x16x32_bf16 v[70:73], v[150:153], v[224:227], v[70:73]
	v_mfma_f32_16x16x32_bf16 v[66:69], v[172:175], v[224:227], v[66:69]
	s_barrier
	s_add_i32 s6, s6, s58
	v_lshl_add_u64 v[180:181], s[54:55], 0, v[158:159]
	s_mov_b32 m0, s6
	ds_read_b128 v[176:179], v185 offset:16384
	ds_read_b128 v[186:189], v185 offset:17408
	ds_read_b128 v[190:193], v185 offset:18432
	ds_read_b128 v[194:197], v185 offset:19456
	ds_read_b128 v[198:201], v185 offset:20480
	ds_read_b128 v[216:219], v185 offset:21504
	ds_read_b128 v[220:223], v185 offset:22528
	ds_read_b128 v[224:227], v185 offset:23552
	global_load_lds_dwordx4 v[180:181], off
	s_add_i32 m0, s6, 0x2000
	s_add_u32 s20, s54, 0xb0000
	v_lshl_add_u64 v[202:203], s[54:55], 0, v[162:163]
	s_addc_u32 s21, s55, 0
	s_add_i32 s6, s26, s58
	global_load_lds_dwordx4 v[202:203], off
	v_lshl_add_u64 v[228:229], s[20:21], 0, v[158:159]
	s_mov_b32 m0, s6
	v_lshl_add_u64 v[230:231], s[56:57], 0, v[160:161]
	global_load_lds_dwordx4 v[228:229], off
	v_lshl_add_u64 v[228:229], s[20:21], 0, v[162:163]
	s_add_i32 m0, s6, 0x2000
	s_nop 0
	global_load_lds_dwordx4 v[228:229], off
	v_lshl_add_u64 v[228:229], s[56:57], 0, v[156:157]
	s_mov_b32 m0, s59
	s_nop 0
	global_load_lds_dwordx4 v[228:229], off
	s_mov_b32 m0, s60
	s_nop 0
	global_load_lds_dwordx4 v[230:231], off
	s_waitcnt vmcnt(8)
	s_waitcnt lgkmcnt(0)
	s_barrier
	v_mfma_f32_16x16x32_bf16 v[62:65], v[122:125], v[176:179], v[62:65]
	v_mfma_f32_16x16x32_bf16 v[58:61], v[138:141], v[176:179], v[58:61]
	v_mfma_f32_16x16x32_bf16 v[44:47], v[122:125], v[190:193], v[44:47]
	v_mfma_f32_16x16x32_bf16 v[40:43], v[138:141], v[190:193], v[40:43]
	v_mfma_f32_16x16x32_bf16 v[28:31], v[122:125], v[198:201], v[28:31]
	v_mfma_f32_16x16x32_bf16 v[24:27], v[138:141], v[198:201], v[24:27]
	v_mfma_f32_16x16x32_bf16 v[12:15], v[122:125], v[220:223], v[12:15]
	v_mfma_f32_16x16x32_bf16 v[8:11], v[138:141], v[220:223], v[8:11]
	v_mfma_f32_16x16x32_bf16 v[62:65], v[130:133], v[186:189], v[62:65]
	v_mfma_f32_16x16x32_bf16 v[58:61], v[142:145], v[186:189], v[58:61]
	v_mfma_f32_16x16x32_bf16 v[44:47], v[130:133], v[194:197], v[44:47]
	v_mfma_f32_16x16x32_bf16 v[40:43], v[142:145], v[194:197], v[40:43]
	v_mfma_f32_16x16x32_bf16 v[28:31], v[130:133], v[216:219], v[28:31]
	v_mfma_f32_16x16x32_bf16 v[24:27], v[142:145], v[216:219], v[24:27]
	v_mfma_f32_16x16x32_bf16 v[12:15], v[130:133], v[224:227], v[12:15]
	v_mfma_f32_16x16x32_bf16 v[8:11], v[142:145], v[224:227], v[8:11]
	v_mfma_f32_16x16x32_bf16 v[54:57], v[146:149], v[176:179], v[54:57]
	v_mfma_f32_16x16x32_bf16 v[50:53], v[168:171], v[176:179], v[50:53]
	v_mfma_f32_16x16x32_bf16 v[36:39], v[146:149], v[190:193], v[36:39]
	v_mfma_f32_16x16x32_bf16 v[32:35], v[168:171], v[190:193], v[32:35]
	v_mfma_f32_16x16x32_bf16 v[20:23], v[146:149], v[198:201], v[20:23]
	v_mfma_f32_16x16x32_bf16 v[16:19], v[168:171], v[198:201], v[16:19]
	v_mfma_f32_16x16x32_bf16 v[4:7], v[146:149], v[220:223], v[4:7]
	v_mfma_f32_16x16x32_bf16 v[0:3], v[168:171], v[220:223], v[0:3]
	v_mfma_f32_16x16x32_bf16 v[54:57], v[150:153], v[186:189], v[54:57]
	v_mfma_f32_16x16x32_bf16 v[50:53], v[172:175], v[186:189], v[50:53]
	v_mfma_f32_16x16x32_bf16 v[36:39], v[150:153], v[194:197], v[36:39]
	v_mfma_f32_16x16x32_bf16 v[32:35], v[172:175], v[194:197], v[32:35]
	v_mfma_f32_16x16x32_bf16 v[20:23], v[150:153], v[216:219], v[20:23]
	v_mfma_f32_16x16x32_bf16 v[16:19], v[172:175], v[216:219], v[16:19]
	v_mfma_f32_16x16x32_bf16 v[4:7], v[150:153], v[224:227], v[4:7]
	v_mfma_f32_16x16x32_bf16 v[0:3], v[172:175], v[224:227], v[0:3]
	s_barrier
	s_add_i32 s6, 0, 0x18000
	v_add_u32_e32 v48, s6, v183
	s_add_i32 s26, 0, 0x1c000
	ds_read_b128 v[122:125], v48
	ds_read_b128 v[130:133], v48 offset:1024
	ds_read_b128 v[138:141], v48 offset:2048
	ds_read_b128 v[142:145], v48 offset:3072
	v_add_u32_e32 v48, s26, v183
	ds_read_b128 v[146:149], v48
	ds_read_b128 v[150:153], v48 offset:1024
	ds_read_b128 v[168:171], v48 offset:2048
	ds_read_b128 v[172:175], v48 offset:3072
	s_add_u32 s20, s56, 0xb0000
	s_addc_u32 s21, s57, 0
	s_mov_b32 m0, s61
	v_lshl_add_u64 v[232:233], s[20:21], 0, v[156:157]
	ds_read_b128 v[176:179], v185 offset:32768
	ds_read_b128 v[186:189], v185 offset:33792
	ds_read_b128 v[190:193], v185 offset:34816
	ds_read_b128 v[194:197], v185 offset:35840
	ds_read_b128 v[198:201], v185 offset:36864
	ds_read_b128 v[216:219], v185 offset:37888
	ds_read_b128 v[220:223], v185 offset:38912
	ds_read_b128 v[224:227], v185 offset:39936
	global_load_lds_dwordx4 v[232:233], off
	v_lshl_add_u64 v[232:233], s[20:21], 0, v[160:161]
	s_mov_b32 m0, s62
	s_nop 0
	global_load_lds_dwordx4 v[232:233], off
	s_waitcnt vmcnt(8)
	s_waitcnt lgkmcnt(0)
	s_barrier
	v_mfma_f32_16x16x32_bf16 v[134:137], v[122:125], v[176:179], v[134:137]
	v_mfma_f32_16x16x32_bf16 v[126:129], v[138:141], v[176:179], v[126:129]
	v_mfma_f32_16x16x32_bf16 v[110:113], v[122:125], v[190:193], v[110:113]
	v_mfma_f32_16x16x32_bf16 v[106:109], v[138:141], v[190:193], v[106:109]
	v_mfma_f32_16x16x32_bf16 v[94:97], v[122:125], v[198:201], v[94:97]
	v_mfma_f32_16x16x32_bf16 v[90:93], v[138:141], v[198:201], v[90:93]
	v_mfma_f32_16x16x32_bf16 v[78:81], v[122:125], v[220:223], v[78:81]
	v_mfma_f32_16x16x32_bf16 v[74:77], v[138:141], v[220:223], v[74:77]
	v_mfma_f32_16x16x32_bf16 v[134:137], v[130:133], v[186:189], v[134:137]
	v_mfma_f32_16x16x32_bf16 v[126:129], v[142:145], v[186:189], v[126:129]
	v_mfma_f32_16x16x32_bf16 v[110:113], v[130:133], v[194:197], v[110:113]
	v_mfma_f32_16x16x32_bf16 v[106:109], v[142:145], v[194:197], v[106:109]
	v_mfma_f32_16x16x32_bf16 v[94:97], v[130:133], v[216:219], v[94:97]
	v_mfma_f32_16x16x32_bf16 v[90:93], v[142:145], v[216:219], v[90:93]
	v_mfma_f32_16x16x32_bf16 v[78:81], v[130:133], v[224:227], v[78:81]
	v_mfma_f32_16x16x32_bf16 v[74:77], v[142:145], v[224:227], v[74:77]
	v_mfma_f32_16x16x32_bf16 v[118:121], v[146:149], v[176:179], v[118:121]
	v_mfma_f32_16x16x32_bf16 v[114:117], v[168:171], v[176:179], v[114:117]
	v_mfma_f32_16x16x32_bf16 v[102:105], v[146:149], v[190:193], v[102:105]
	v_mfma_f32_16x16x32_bf16 v[98:101], v[168:171], v[190:193], v[98:101]
	v_mfma_f32_16x16x32_bf16 v[86:89], v[146:149], v[198:201], v[86:89]
	v_mfma_f32_16x16x32_bf16 v[82:85], v[168:171], v[198:201], v[82:85]
	v_mfma_f32_16x16x32_bf16 v[70:73], v[146:149], v[220:223], v[70:73]
	v_mfma_f32_16x16x32_bf16 v[66:69], v[168:171], v[220:223], v[66:69]
	v_mfma_f32_16x16x32_bf16 v[118:121], v[150:153], v[186:189], v[118:121]
	v_mfma_f32_16x16x32_bf16 v[114:117], v[172:175], v[186:189], v[114:117]
	v_mfma_f32_16x16x32_bf16 v[102:105], v[150:153], v[194:197], v[102:105]
	v_mfma_f32_16x16x32_bf16 v[98:101], v[172:175], v[194:197], v[98:101]
	v_mfma_f32_16x16x32_bf16 v[86:89], v[150:153], v[216:219], v[86:89]
	v_mfma_f32_16x16x32_bf16 v[82:85], v[172:175], v[216:219], v[82:85]
	v_mfma_f32_16x16x32_bf16 v[70:73], v[150:153], v[224:227], v[70:73]
	v_mfma_f32_16x16x32_bf16 v[66:69], v[172:175], v[224:227], v[66:69]
	s_barrier
	s_add_i32 s6, s6, s58
	v_lshl_add_u64 v[180:181], v[180:181], 0, s[30:31]
	s_mov_b32 m0, s6
	ds_read_b128 v[176:179], v185 offset:49152
	ds_read_b128 v[186:189], v185 offset:50176
	ds_read_b128 v[190:193], v185 offset:51200
	ds_read_b128 v[194:197], v185 offset:52224
	ds_read_b128 v[198:201], v185 offset:53248
	ds_read_b128 v[216:219], v185 offset:54272
	ds_read_b128 v[220:223], v185 offset:55296
	ds_read_b128 v[224:227], v185 offset:56320
	global_load_lds_dwordx4 v[180:181], off
	s_add_i32 m0, s6, 0x2000
	s_add_u32 s20, s54, 0xb0080
	v_lshl_add_u64 v[180:181], v[202:203], 0, s[30:31]
	s_addc_u32 s21, s55, 0
	s_add_i32 s6, s26, s58
	global_load_lds_dwordx4 v[180:181], off
	v_lshl_add_u64 v[180:181], s[20:21], 0, v[158:159]
	s_mov_b32 m0, s6
	s_nop 0
	global_load_lds_dwordx4 v[180:181], off
	v_lshl_add_u64 v[180:181], s[20:21], 0, v[162:163]
	s_add_i32 m0, s6, 0x2000
	s_nop 0
	global_load_lds_dwordx4 v[180:181], off
	v_lshl_add_u64 v[180:181], v[228:229], 0, s[30:31]
	s_mov_b32 m0, s63
	s_nop 0
	global_load_lds_dwordx4 v[180:181], off
	v_lshl_add_u64 v[180:181], v[230:231], 0, s[30:31]
	s_mov_b32 m0, s64
	s_nop 0
	global_load_lds_dwordx4 v[180:181], off
	s_waitcnt vmcnt(8)
	s_waitcnt lgkmcnt(0)
	s_barrier
	v_mfma_f32_16x16x32_bf16 v[62:65], v[122:125], v[176:179], v[62:65]
	v_mfma_f32_16x16x32_bf16 v[58:61], v[138:141], v[176:179], v[58:61]
	v_mfma_f32_16x16x32_bf16 v[44:47], v[122:125], v[190:193], v[44:47]
	v_mfma_f32_16x16x32_bf16 v[40:43], v[138:141], v[190:193], v[40:43]
	v_mfma_f32_16x16x32_bf16 v[28:31], v[122:125], v[198:201], v[28:31]
	v_mfma_f32_16x16x32_bf16 v[24:27], v[138:141], v[198:201], v[24:27]
	v_mfma_f32_16x16x32_bf16 v[12:15], v[122:125], v[220:223], v[12:15]
	v_mfma_f32_16x16x32_bf16 v[8:11], v[138:141], v[220:223], v[8:11]
	v_mfma_f32_16x16x32_bf16 v[62:65], v[130:133], v[186:189], v[62:65]
	v_mfma_f32_16x16x32_bf16 v[58:61], v[142:145], v[186:189], v[58:61]
	v_mfma_f32_16x16x32_bf16 v[44:47], v[130:133], v[194:197], v[44:47]
	v_mfma_f32_16x16x32_bf16 v[40:43], v[142:145], v[194:197], v[40:43]
	v_mfma_f32_16x16x32_bf16 v[28:31], v[130:133], v[216:219], v[28:31]
	v_mfma_f32_16x16x32_bf16 v[24:27], v[142:145], v[216:219], v[24:27]
	v_mfma_f32_16x16x32_bf16 v[12:15], v[130:133], v[224:227], v[12:15]
	v_mfma_f32_16x16x32_bf16 v[8:11], v[142:145], v[224:227], v[8:11]
	v_mfma_f32_16x16x32_bf16 v[54:57], v[146:149], v[176:179], v[54:57]
	v_mfma_f32_16x16x32_bf16 v[50:53], v[168:171], v[176:179], v[50:53]
	v_mfma_f32_16x16x32_bf16 v[36:39], v[146:149], v[190:193], v[36:39]
	v_mfma_f32_16x16x32_bf16 v[32:35], v[168:171], v[190:193], v[32:35]
	v_mfma_f32_16x16x32_bf16 v[20:23], v[146:149], v[198:201], v[20:23]
	v_mfma_f32_16x16x32_bf16 v[16:19], v[168:171], v[198:201], v[16:19]
	v_mfma_f32_16x16x32_bf16 v[4:7], v[146:149], v[220:223], v[4:7]
	v_mfma_f32_16x16x32_bf16 v[0:3], v[168:171], v[220:223], v[0:3]
	v_mfma_f32_16x16x32_bf16 v[54:57], v[150:153], v[186:189], v[54:57]
	v_mfma_f32_16x16x32_bf16 v[50:53], v[172:175], v[186:189], v[50:53]
	v_mfma_f32_16x16x32_bf16 v[36:39], v[150:153], v[194:197], v[36:39]
	v_mfma_f32_16x16x32_bf16 v[32:35], v[172:175], v[194:197], v[32:35]
	v_mfma_f32_16x16x32_bf16 v[20:23], v[150:153], v[216:219], v[20:23]
	v_mfma_f32_16x16x32_bf16 v[16:19], v[172:175], v[216:219], v[16:19]
	v_mfma_f32_16x16x32_bf16 v[4:7], v[150:153], v[224:227], v[4:7]
	v_mfma_f32_16x16x32_bf16 v[0:3], v[172:175], v[224:227], v[0:3]
	s_barrier
	s_add_i32 s71, s71, 2
	s_add_u32 s69, s69, 0x100
	s_addc_u32 s70, s70, 0
	s_cmp_gt_u32 s71, 41
	s_mov_b64 s[50:51], s[52:53]
	s_cbranch_scc0 .LBB0_472
	s_and_b64 vcc, exec, s[44:45]
	s_cbranch_vccz .LBB0_475
	s_barrier

.LBB0_585:
	s_add_u32 s6, s60, 0xfffc0080
	s_addc_u32 s20, s61, -1
	s_add_i32 s21, 0, 0x10000
	s_cmp_eq_u32 s90, 12
	s_cselect_b32 s65, s18, s20
	s_cselect_b32 s64, s33, s6
	v_add_u32_e32 v48, s21, v175
	s_cselect_b32 s63, s43, s53
	s_cselect_b32 s62, s45, s51
	s_add_i32 s6, 0, 0x14000
	ds_read_b128 v[142:145], v48
	ds_read_b128 v[146:149], v48 offset:1024
	ds_read_b128 v[150:153], v48 offset:2048
	ds_read_b128 v[156:159], v48 offset:3072
	v_add_u32_e32 v48, s6, v175
	ds_read_b128 v[160:163], v48
	ds_read_b128 v[164:167], v48 offset:1024
	ds_read_b128 v[168:171], v48 offset:2048
	ds_read_b128 v[180:183], v48 offset:3072
	v_lshl_add_u64 v[172:173], s[60:61], 0, v[138:139]
	s_add_i32 m0, s66, 0xc000
	ds_read_b128 v[184:187], v178
	ds_read_b128 v[188:191], v178 offset:1024
	ds_read_b128 v[192:195], v178 offset:2048
	ds_read_b128 v[196:199], v178 offset:3072
	ds_read_b128 v[200:203], v178 offset:4096
	ds_read_b128 v[216:219], v178 offset:5120
	ds_read_b128 v[220:223], v178 offset:6144
	ds_read_b128 v[224:227], v178 offset:7168
	global_load_lds_dwordx4 v[172:173], off
	v_lshl_add_u64 v[172:173], s[60:61], 0, v[140:141]
	s_add_i32 m0, s66, 0xe000
	s_nop 0
	global_load_lds_dwordx4 v[172:173], off
	s_waitcnt vmcnt(8)
	s_waitcnt lgkmcnt(0)
	s_barrier
	v_mfma_f32_16x16x32_bf16 v[126:129], v[142:145], v[184:187], v[126:129]
	v_mfma_f32_16x16x32_bf16 v[122:125], v[150:153], v[184:187], v[122:125]
	v_mfma_f32_16x16x32_bf16 v[110:113], v[142:145], v[192:195], v[110:113]
	v_mfma_f32_16x16x32_bf16 v[106:109], v[150:153], v[192:195], v[106:109]
	v_mfma_f32_16x16x32_bf16 v[94:97], v[142:145], v[200:203], v[94:97]
	v_mfma_f32_16x16x32_bf16 v[90:93], v[150:153], v[200:203], v[90:93]
	v_mfma_f32_16x16x32_bf16 v[78:81], v[142:145], v[220:223], v[78:81]
	v_mfma_f32_16x16x32_bf16 v[74:77], v[150:153], v[220:223], v[74:77]
	v_mfma_f32_16x16x32_bf16 v[126:129], v[146:149], v[188:191], v[126:129]
	v_mfma_f32_16x16x32_bf16 v[122:125], v[156:159], v[188:191], v[122:125]
	v_mfma_f32_16x16x32_bf16 v[110:113], v[146:149], v[196:199], v[110:113]
	v_mfma_f32_16x16x32_bf16 v[106:109], v[156:159], v[196:199], v[106:109]
	v_mfma_f32_16x16x32_bf16 v[94:97], v[146:149], v[216:219], v[94:97]
	v_mfma_f32_16x16x32_bf16 v[90:93], v[156:159], v[216:219], v[90:93]
	v_mfma_f32_16x16x32_bf16 v[78:81], v[146:149], v[224:227], v[78:81]
	v_mfma_f32_16x16x32_bf16 v[74:77], v[156:159], v[224:227], v[74:77]
	v_mfma_f32_16x16x32_bf16 v[118:121], v[160:163], v[184:187], v[118:121]
	v_mfma_f32_16x16x32_bf16 v[114:117], v[168:171], v[184:187], v[114:117]
	v_mfma_f32_16x16x32_bf16 v[102:105], v[160:163], v[192:195], v[102:105]
	v_mfma_f32_16x16x32_bf16 v[98:101], v[168:171], v[192:195], v[98:101]
	v_mfma_f32_16x16x32_bf16 v[86:89], v[160:163], v[200:203], v[86:89]
	v_mfma_f32_16x16x32_bf16 v[82:85], v[168:171], v[200:203], v[82:85]
	v_mfma_f32_16x16x32_bf16 v[70:73], v[160:163], v[220:223], v[70:73]
	v_mfma_f32_16x16x32_bf16 v[66:69], v[168:171], v[220:223], v[66:69]
	v_mfma_f32_16x16x32_bf16 v[118:121], v[164:167], v[188:191], v[118:121]
	v_mfma_f32_16x16x32_bf16 v[114:117], v[180:183], v[188:191], v[114:117]
	v_mfma_f32_16x16x32_bf16 v[102:105], v[164:167], v[196:199], v[102:105]
	v_mfma_f32_16x16x32_bf16 v[98:101], v[180:183], v[196:199], v[98:101]
	v_mfma_f32_16x16x32_bf16 v[86:89], v[164:167], v[216:219], v[86:89]
	v_mfma_f32_16x16x32_bf16 v[82:85], v[180:183], v[216:219], v[82:85]
	v_mfma_f32_16x16x32_bf16 v[70:73], v[164:167], v[224:227], v[70:73]
	v_mfma_f32_16x16x32_bf16 v[66:69], v[180:183], v[224:227], v[66:69]
	s_barrier
	s_add_i32 s20, s21, s24
	v_lshl_add_u64 v[172:173], s[62:63], 0, v[132:133]
	s_mov_b32 m0, s20
	ds_read_b128 v[184:187], v178 offset:16384
	ds_read_b128 v[188:191], v178 offset:17408
	ds_read_b128 v[192:195], v178 offset:18432
	ds_read_b128 v[196:199], v178 offset:19456
	ds_read_b128 v[200:203], v178 offset:20480
	ds_read_b128 v[216:219], v178 offset:21504
	ds_read_b128 v[220:223], v178 offset:22528
	ds_read_b128 v[224:227], v178 offset:23552
	global_load_lds_dwordx4 v[172:173], off
	s_add_i32 m0, s20, 0x2000
	s_add_u32 s20, s62, 0x40000
	v_lshl_add_u64 v[228:229], s[62:63], 0, v[136:137]
	s_addc_u32 s21, s63, 0
	s_add_i32 s6, s6, s24
	global_load_lds_dwordx4 v[228:229], off
	v_lshl_add_u64 v[230:231], s[20:21], 0, v[132:133]
	s_mov_b32 m0, s6
	v_lshl_add_u64 v[232:233], s[64:65], 0, v[134:135]
	global_load_lds_dwordx4 v[230:231], off
	v_lshl_add_u64 v[230:231], s[20:21], 0, v[136:137]
	s_add_i32 m0, s6, 0x2000
	s_nop 0
	global_load_lds_dwordx4 v[230:231], off
	v_lshl_add_u64 v[230:231], s[64:65], 0, v[130:131]
	s_mov_b32 m0, s66
	s_nop 0
	global_load_lds_dwordx4 v[230:231], off
	s_mov_b32 m0, s67
	s_nop 0
	global_load_lds_dwordx4 v[232:233], off
	s_waitcnt vmcnt(8)
	s_waitcnt lgkmcnt(0)
	s_barrier
	v_mfma_f32_16x16x32_bf16 v[62:65], v[142:145], v[184:187], v[62:65]
	v_mfma_f32_16x16x32_bf16 v[58:61], v[150:153], v[184:187], v[58:61]
	v_mfma_f32_16x16x32_bf16 v[44:47], v[142:145], v[192:195], v[44:47]
	v_mfma_f32_16x16x32_bf16 v[40:43], v[150:153], v[192:195], v[40:43]
	v_mfma_f32_16x16x32_bf16 v[28:31], v[142:145], v[200:203], v[28:31]
	v_mfma_f32_16x16x32_bf16 v[24:27], v[150:153], v[200:203], v[24:27]
	v_mfma_f32_16x16x32_bf16 v[12:15], v[142:145], v[220:223], v[12:15]
	v_mfma_f32_16x16x32_bf16 v[8:11], v[150:153], v[220:223], v[8:11]
	v_mfma_f32_16x16x32_bf16 v[62:65], v[146:149], v[188:191], v[62:65]
	v_mfma_f32_16x16x32_bf16 v[58:61], v[156:159], v[188:191], v[58:61]
	v_mfma_f32_16x16x32_bf16 v[44:47], v[146:149], v[196:199], v[44:47]
	v_mfma_f32_16x16x32_bf16 v[40:43], v[156:159], v[196:199], v[40:43]
	v_mfma_f32_16x16x32_bf16 v[28:31], v[146:149], v[216:219], v[28:31]
	v_mfma_f32_16x16x32_bf16 v[24:27], v[156:159], v[216:219], v[24:27]
	v_mfma_f32_16x16x32_bf16 v[12:15], v[146:149], v[224:227], v[12:15]
	v_mfma_f32_16x16x32_bf16 v[8:11], v[156:159], v[224:227], v[8:11]
	v_mfma_f32_16x16x32_bf16 v[54:57], v[160:163], v[184:187], v[54:57]
	v_mfma_f32_16x16x32_bf16 v[50:53], v[168:171], v[184:187], v[50:53]
	v_mfma_f32_16x16x32_bf16 v[36:39], v[160:163], v[192:195], v[36:39]
	v_mfma_f32_16x16x32_bf16 v[32:35], v[168:171], v[192:195], v[32:35]
	v_mfma_f32_16x16x32_bf16 v[20:23], v[160:163], v[200:203], v[20:23]
	v_mfma_f32_16x16x32_bf16 v[16:19], v[168:171], v[200:203], v[16:19]
	v_mfma_f32_16x16x32_bf16 v[4:7], v[160:163], v[220:223], v[4:7]
	v_mfma_f32_16x16x32_bf16 v[0:3], v[168:171], v[220:223], v[0:3]
	v_mfma_f32_16x16x32_bf16 v[54:57], v[164:167], v[188:191], v[54:57]
	v_mfma_f32_16x16x32_bf16 v[50:53], v[180:183], v[188:191], v[50:53]
	v_mfma_f32_16x16x32_bf16 v[36:39], v[164:167], v[196:199], v[36:39]
	v_mfma_f32_16x16x32_bf16 v[32:35], v[180:183], v[196:199], v[32:35]
	v_mfma_f32_16x16x32_bf16 v[20:23], v[164:167], v[216:219], v[20:23]
	v_mfma_f32_16x16x32_bf16 v[16:19], v[180:183], v[216:219], v[16:19]
	v_mfma_f32_16x16x32_bf16 v[4:7], v[164:167], v[224:227], v[4:7]
	v_mfma_f32_16x16x32_bf16 v[0:3], v[180:183], v[224:227], v[0:3]
	s_barrier
	s_add_i32 s6, 0, 0x18000
	v_add_u32_e32 v48, s6, v175
	s_add_i32 s26, 0, 0x1c000
	ds_read_b128 v[142:145], v48
	ds_read_b128 v[146:149], v48 offset:1024
	ds_read_b128 v[150:153], v48 offset:2048
	ds_read_b128 v[156:159], v48 offset:3072
	v_add_u32_e32 v48, s26, v175
	ds_read_b128 v[160:163], v48
	ds_read_b128 v[164:167], v48 offset:1024
	ds_read_b128 v[168:171], v48 offset:2048
	ds_read_b128 v[180:183], v48 offset:3072
	s_add_u32 s20, s64, 0x40000
	s_addc_u32 s21, s65, 0
	s_mov_b32 m0, s68
	v_lshl_add_u64 v[234:235], s[20:21], 0, v[130:131]
	ds_read_b128 v[184:187], v178 offset:32768
	ds_read_b128 v[188:191], v178 offset:33792
	ds_read_b128 v[192:195], v178 offset:34816
	ds_read_b128 v[196:199], v178 offset:35840
	ds_read_b128 v[200:203], v178 offset:36864
	ds_read_b128 v[216:219], v178 offset:37888
	ds_read_b128 v[220:223], v178 offset:38912
	ds_read_b128 v[224:227], v178 offset:39936
	global_load_lds_dwordx4 v[234:235], off
	v_lshl_add_u64 v[234:235], s[20:21], 0, v[134:135]
	s_mov_b32 m0, s69
	s_nop 0
	global_load_lds_dwordx4 v[234:235], off
	s_waitcnt vmcnt(8)
	s_waitcnt lgkmcnt(0)
	s_barrier
	v_mfma_f32_16x16x32_bf16 v[126:129], v[142:145], v[184:187], v[126:129]
	v_mfma_f32_16x16x32_bf16 v[122:125], v[150:153], v[184:187], v[122:125]
	v_mfma_f32_16x16x32_bf16 v[110:113], v[142:145], v[192:195], v[110:113]
	v_mfma_f32_16x16x32_bf16 v[106:109], v[150:153], v[192:195], v[106:109]
	v_mfma_f32_16x16x32_bf16 v[94:97], v[142:145], v[200:203], v[94:97]
	v_mfma_f32_16x16x32_bf16 v[90:93], v[150:153], v[200:203], v[90:93]
	v_mfma_f32_16x16x32_bf16 v[78:81], v[142:145], v[220:223], v[78:81]
	v_mfma_f32_16x16x32_bf16 v[74:77], v[150:153], v[220:223], v[74:77]
	v_mfma_f32_16x16x32_bf16 v[126:129], v[146:149], v[188:191], v[126:129]
	v_mfma_f32_16x16x32_bf16 v[122:125], v[156:159], v[188:191], v[122:125]
	v_mfma_f32_16x16x32_bf16 v[110:113], v[146:149], v[196:199], v[110:113]
	v_mfma_f32_16x16x32_bf16 v[106:109], v[156:159], v[196:199], v[106:109]
	v_mfma_f32_16x16x32_bf16 v[94:97], v[146:149], v[216:219], v[94:97]
	v_mfma_f32_16x16x32_bf16 v[90:93], v[156:159], v[216:219], v[90:93]
	v_mfma_f32_16x16x32_bf16 v[78:81], v[146:149], v[224:227], v[78:81]
	v_mfma_f32_16x16x32_bf16 v[74:77], v[156:159], v[224:227], v[74:77]
	v_mfma_f32_16x16x32_bf16 v[118:121], v[160:163], v[184:187], v[118:121]
	v_mfma_f32_16x16x32_bf16 v[114:117], v[168:171], v[184:187], v[114:117]
	v_mfma_f32_16x16x32_bf16 v[102:105], v[160:163], v[192:195], v[102:105]
	v_mfma_f32_16x16x32_bf16 v[98:101], v[168:171], v[192:195], v[98:101]
	v_mfma_f32_16x16x32_bf16 v[86:89], v[160:163], v[200:203], v[86:89]
	v_mfma_f32_16x16x32_bf16 v[82:85], v[168:171], v[200:203], v[82:85]
	v_mfma_f32_16x16x32_bf16 v[70:73], v[160:163], v[220:223], v[70:73]
	v_mfma_f32_16x16x32_bf16 v[66:69], v[168:171], v[220:223], v[66:69]
	v_mfma_f32_16x16x32_bf16 v[118:121], v[164:167], v[188:191], v[118:121]
	v_mfma_f32_16x16x32_bf16 v[114:117], v[180:183], v[188:191], v[114:117]
	v_mfma_f32_16x16x32_bf16 v[102:105], v[164:167], v[196:199], v[102:105]
	v_mfma_f32_16x16x32_bf16 v[98:101], v[180:183], v[196:199], v[98:101]
	v_mfma_f32_16x16x32_bf16 v[86:89], v[164:167], v[216:219], v[86:89]
	v_mfma_f32_16x16x32_bf16 v[82:85], v[180:183], v[216:219], v[82:85]
	v_mfma_f32_16x16x32_bf16 v[70:73], v[164:167], v[224:227], v[70:73]
	v_mfma_f32_16x16x32_bf16 v[66:69], v[180:183], v[224:227], v[66:69]
	s_barrier
	s_add_i32 s6, s6, s24
	v_lshl_add_u64 v[172:173], v[172:173], 0, s[30:31]
	s_mov_b32 m0, s6
	ds_read_b128 v[184:187], v178 offset:49152
	ds_read_b128 v[188:191], v178 offset:50176
	ds_read_b128 v[192:195], v178 offset:51200
	ds_read_b128 v[196:199], v178 offset:52224
	ds_read_b128 v[200:203], v178 offset:53248
	ds_read_b128 v[216:219], v178 offset:54272
	ds_read_b128 v[220:223], v178 offset:55296
	ds_read_b128 v[224:227], v178 offset:56320
	global_load_lds_dwordx4 v[172:173], off
	s_add_i32 m0, s6, 0x2000
	s_add_u32 s20, s62, 0x40080
	v_lshl_add_u64 v[172:173], v[228:229], 0, s[30:31]
	s_addc_u32 s21, s63, 0
	s_add_i32 s6, s26, s24
	global_load_lds_dwordx4 v[172:173], off
	v_lshl_add_u64 v[172:173], s[20:21], 0, v[132:133]
	s_mov_b32 m0, s6
	s_nop 0
	global_load_lds_dwordx4 v[172:173], off
	v_lshl_add_u64 v[172:173], s[20:21], 0, v[136:137]
	s_add_i32 m0, s6, 0x2000
	s_nop 0
	global_load_lds_dwordx4 v[172:173], off
	v_lshl_add_u64 v[172:173], v[230:231], 0, s[30:31]
	s_mov_b32 m0, s70
	s_nop 0
	global_load_lds_dwordx4 v[172:173], off
	v_lshl_add_u64 v[172:173], v[232:233], 0, s[30:31]
	s_mov_b32 m0, s71
	s_nop 0
	global_load_lds_dwordx4 v[172:173], off
	s_waitcnt vmcnt(8)
	s_waitcnt lgkmcnt(0)
	s_barrier
	v_mfma_f32_16x16x32_bf16 v[62:65], v[142:145], v[184:187], v[62:65]
	v_mfma_f32_16x16x32_bf16 v[58:61], v[150:153], v[184:187], v[58:61]
	v_mfma_f32_16x16x32_bf16 v[44:47], v[142:145], v[192:195], v[44:47]
	v_mfma_f32_16x16x32_bf16 v[40:43], v[150:153], v[192:195], v[40:43]
	v_mfma_f32_16x16x32_bf16 v[28:31], v[142:145], v[200:203], v[28:31]
	v_mfma_f32_16x16x32_bf16 v[24:27], v[150:153], v[200:203], v[24:27]
	v_mfma_f32_16x16x32_bf16 v[12:15], v[142:145], v[220:223], v[12:15]
	v_mfma_f32_16x16x32_bf16 v[8:11], v[150:153], v[220:223], v[8:11]
	v_mfma_f32_16x16x32_bf16 v[62:65], v[146:149], v[188:191], v[62:65]
	v_mfma_f32_16x16x32_bf16 v[58:61], v[156:159], v[188:191], v[58:61]
	v_mfma_f32_16x16x32_bf16 v[44:47], v[146:149], v[196:199], v[44:47]
	v_mfma_f32_16x16x32_bf16 v[40:43], v[156:159], v[196:199], v[40:43]
	v_mfma_f32_16x16x32_bf16 v[28:31], v[146:149], v[216:219], v[28:31]
	v_mfma_f32_16x16x32_bf16 v[24:27], v[156:159], v[216:219], v[24:27]
	v_mfma_f32_16x16x32_bf16 v[12:15], v[146:149], v[224:227], v[12:15]
	v_mfma_f32_16x16x32_bf16 v[8:11], v[156:159], v[224:227], v[8:11]
	v_mfma_f32_16x16x32_bf16 v[54:57], v[160:163], v[184:187], v[54:57]
	v_mfma_f32_16x16x32_bf16 v[50:53], v[168:171], v[184:187], v[50:53]
	v_mfma_f32_16x16x32_bf16 v[36:39], v[160:163], v[192:195], v[36:39]
	v_mfma_f32_16x16x32_bf16 v[32:35], v[168:171], v[192:195], v[32:35]
	v_mfma_f32_16x16x32_bf16 v[20:23], v[160:163], v[200:203], v[20:23]
	v_mfma_f32_16x16x32_bf16 v[16:19], v[168:171], v[200:203], v[16:19]
	v_mfma_f32_16x16x32_bf16 v[4:7], v[160:163], v[220:223], v[4:7]
	v_mfma_f32_16x16x32_bf16 v[0:3], v[168:171], v[220:223], v[0:3]
	v_mfma_f32_16x16x32_bf16 v[54:57], v[164:167], v[188:191], v[54:57]
	v_mfma_f32_16x16x32_bf16 v[50:53], v[180:183], v[188:191], v[50:53]
	v_mfma_f32_16x16x32_bf16 v[36:39], v[164:167], v[196:199], v[36:39]
	v_mfma_f32_16x16x32_bf16 v[32:35], v[180:183], v[196:199], v[32:35]
	v_mfma_f32_16x16x32_bf16 v[20:23], v[164:167], v[216:219], v[20:23]
	v_mfma_f32_16x16x32_bf16 v[16:19], v[180:183], v[216:219], v[16:19]
	v_mfma_f32_16x16x32_bf16 v[4:7], v[164:167], v[224:227], v[4:7]
	v_mfma_f32_16x16x32_bf16 v[0:3], v[180:183], v[224:227], v[0:3]
	s_barrier
	s_add_i32 s90, s90, 2
	s_add_u32 s60, s60, 0x100
	s_addc_u32 s61, s61, 0
	s_add_u32 s51, s51, 0x100
	s_addc_u32 s53, s53, 0
	s_cmp_gt_u32 s90, 13
	s_cbranch_scc0 .LBB0_585
	s_and_b64 vcc, exec, s[48:49]
	s_cbranch_vccz .LBB0_588
	s_barrier

.LBB0_690:
	s_add_u32 s6, s56, 0xfffc0080
	s_addc_u32 s20, s57, -1
	s_add_i32 s21, 0, 0x10000
	s_cmp_eq_u32 s71, 12
	s_cselect_b32 s61, s41, s20
	s_cselect_b32 s60, s47, s6
	v_add_u32_e32 v48, s21, v177
	s_cselect_b32 s59, s49, s70
	s_cselect_b32 s58, s68, s69
	s_add_i32 s6, 0, 0x14000
	ds_read_b128 v[142:145], v48
	ds_read_b128 v[146:149], v48 offset:1024
	ds_read_b128 v[150:153], v48 offset:2048
	ds_read_b128 v[156:159], v48 offset:3072
	v_add_u32_e32 v48, s6, v177
	ds_read_b128 v[160:163], v48
	ds_read_b128 v[164:167], v48 offset:1024
	ds_read_b128 v[168:171], v48 offset:2048
	ds_read_b128 v[172:175], v48 offset:3072
	v_lshl_add_u64 v[202:203], s[56:57], 0, v[138:139]
	s_add_i32 m0, s63, 0xc000
	ds_read_b128 v[182:185], v180
	ds_read_b128 v[186:189], v180 offset:1024
	ds_read_b128 v[190:193], v180 offset:2048
	ds_read_b128 v[194:197], v180 offset:3072
	ds_read_b128 v[198:201], v180 offset:4096
	ds_read_b128 v[216:219], v180 offset:5120
	ds_read_b128 v[220:223], v180 offset:6144
	ds_read_b128 v[224:227], v180 offset:7168
	global_load_lds_dwordx4 v[202:203], off
	v_lshl_add_u64 v[202:203], s[56:57], 0, v[140:141]
	s_add_i32 m0, s63, 0xe000
	s_nop 0
	global_load_lds_dwordx4 v[202:203], off
	s_waitcnt vmcnt(8)
	s_waitcnt lgkmcnt(0)
	s_barrier
	v_mfma_f32_16x16x32_bf16 v[126:129], v[142:145], v[182:185], v[126:129]
	v_mfma_f32_16x16x32_bf16 v[122:125], v[150:153], v[182:185], v[122:125]
	v_mfma_f32_16x16x32_bf16 v[118:121], v[142:145], v[190:193], v[118:121]
	v_mfma_f32_16x16x32_bf16 v[110:113], v[150:153], v[190:193], v[110:113]
	v_mfma_f32_16x16x32_bf16 v[102:105], v[142:145], v[198:201], v[102:105]
	v_mfma_f32_16x16x32_bf16 v[94:97], v[150:153], v[198:201], v[94:97]
	v_mfma_f32_16x16x32_bf16 v[86:89], v[142:145], v[220:223], v[86:89]
	v_mfma_f32_16x16x32_bf16 v[78:81], v[150:153], v[220:223], v[78:81]
	v_mfma_f32_16x16x32_bf16 v[126:129], v[146:149], v[186:189], v[126:129]
	v_mfma_f32_16x16x32_bf16 v[122:125], v[156:159], v[186:189], v[122:125]
	v_mfma_f32_16x16x32_bf16 v[118:121], v[146:149], v[194:197], v[118:121]
	v_mfma_f32_16x16x32_bf16 v[110:113], v[156:159], v[194:197], v[110:113]
	v_mfma_f32_16x16x32_bf16 v[102:105], v[146:149], v[216:219], v[102:105]
	v_mfma_f32_16x16x32_bf16 v[94:97], v[156:159], v[216:219], v[94:97]
	v_mfma_f32_16x16x32_bf16 v[86:89], v[146:149], v[224:227], v[86:89]
	v_mfma_f32_16x16x32_bf16 v[78:81], v[156:159], v[224:227], v[78:81]
	v_mfma_f32_16x16x32_bf16 v[114:117], v[160:163], v[182:185], v[114:117]
	v_mfma_f32_16x16x32_bf16 v[106:109], v[168:171], v[182:185], v[106:109]
	v_mfma_f32_16x16x32_bf16 v[98:101], v[160:163], v[190:193], v[98:101]
	v_mfma_f32_16x16x32_bf16 v[90:93], v[168:171], v[190:193], v[90:93]
	v_mfma_f32_16x16x32_bf16 v[82:85], v[160:163], v[198:201], v[82:85]
	v_mfma_f32_16x16x32_bf16 v[74:77], v[168:171], v[198:201], v[74:77]
	v_mfma_f32_16x16x32_bf16 v[70:73], v[160:163], v[220:223], v[70:73]
	v_mfma_f32_16x16x32_bf16 v[66:69], v[168:171], v[220:223], v[66:69]
	v_mfma_f32_16x16x32_bf16 v[114:117], v[164:167], v[186:189], v[114:117]
	v_mfma_f32_16x16x32_bf16 v[106:109], v[172:175], v[186:189], v[106:109]
	v_mfma_f32_16x16x32_bf16 v[98:101], v[164:167], v[194:197], v[98:101]
	v_mfma_f32_16x16x32_bf16 v[90:93], v[172:175], v[194:197], v[90:93]
	v_mfma_f32_16x16x32_bf16 v[82:85], v[164:167], v[216:219], v[82:85]
	v_mfma_f32_16x16x32_bf16 v[74:77], v[172:175], v[216:219], v[74:77]
	v_mfma_f32_16x16x32_bf16 v[70:73], v[164:167], v[224:227], v[70:73]
	v_mfma_f32_16x16x32_bf16 v[66:69], v[172:175], v[224:227], v[66:69]
	s_barrier
	s_add_i32 s20, s21, s62
	v_lshl_add_u64 v[202:203], s[58:59], 0, v[134:135]
	s_mov_b32 m0, s20
	ds_read_b128 v[182:185], v180 offset:16384
	ds_read_b128 v[186:189], v180 offset:17408
	ds_read_b128 v[190:193], v180 offset:18432
	ds_read_b128 v[194:197], v180 offset:19456
	ds_read_b128 v[198:201], v180 offset:20480
	ds_read_b128 v[216:219], v180 offset:21504
	ds_read_b128 v[220:223], v180 offset:22528
	ds_read_b128 v[224:227], v180 offset:23552
	global_load_lds_dwordx4 v[202:203], off
	s_add_i32 m0, s20, 0x2000
	s_add_u32 s20, s58, 0x40000
	v_lshl_add_u64 v[228:229], s[58:59], 0, v[130:131]
	s_addc_u32 s21, s59, 0
	s_add_i32 s6, s6, s62
	global_load_lds_dwordx4 v[228:229], off
	v_lshl_add_u64 v[230:231], s[20:21], 0, v[134:135]
	s_mov_b32 m0, s6
	v_lshl_add_u64 v[232:233], s[60:61], 0, v[132:133]
	global_load_lds_dwordx4 v[230:231], off
	v_lshl_add_u64 v[230:231], s[20:21], 0, v[130:131]
	s_add_i32 m0, s6, 0x2000
	s_nop 0
	global_load_lds_dwordx4 v[230:231], off
	v_lshl_add_u64 v[230:231], s[60:61], 0, v[136:137]
	s_mov_b32 m0, s63
	s_nop 0
	global_load_lds_dwordx4 v[230:231], off
	s_mov_b32 m0, s64
	s_nop 0
	global_load_lds_dwordx4 v[232:233], off
	s_waitcnt vmcnt(8)
	s_waitcnt lgkmcnt(0)
	s_barrier
	v_mfma_f32_16x16x32_bf16 v[62:65], v[142:145], v[182:185], v[62:65]
	v_mfma_f32_16x16x32_bf16 v[58:61], v[150:153], v[182:185], v[58:61]
	v_mfma_f32_16x16x32_bf16 v[54:57], v[142:145], v[190:193], v[54:57]
	v_mfma_f32_16x16x32_bf16 v[44:47], v[150:153], v[190:193], v[44:47]
	v_mfma_f32_16x16x32_bf16 v[36:39], v[142:145], v[198:201], v[36:39]
	v_mfma_f32_16x16x32_bf16 v[28:31], v[150:153], v[198:201], v[28:31]
	v_mfma_f32_16x16x32_bf16 v[20:23], v[142:145], v[220:223], v[20:23]
	v_mfma_f32_16x16x32_bf16 v[12:15], v[150:153], v[220:223], v[12:15]
	v_mfma_f32_16x16x32_bf16 v[62:65], v[146:149], v[186:189], v[62:65]
	v_mfma_f32_16x16x32_bf16 v[58:61], v[156:159], v[186:189], v[58:61]
	v_mfma_f32_16x16x32_bf16 v[54:57], v[146:149], v[194:197], v[54:57]
	v_mfma_f32_16x16x32_bf16 v[44:47], v[156:159], v[194:197], v[44:47]
	v_mfma_f32_16x16x32_bf16 v[36:39], v[146:149], v[216:219], v[36:39]
	v_mfma_f32_16x16x32_bf16 v[28:31], v[156:159], v[216:219], v[28:31]
	v_mfma_f32_16x16x32_bf16 v[20:23], v[146:149], v[224:227], v[20:23]
	v_mfma_f32_16x16x32_bf16 v[12:15], v[156:159], v[224:227], v[12:15]
	v_mfma_f32_16x16x32_bf16 v[50:53], v[160:163], v[182:185], v[50:53]
	v_mfma_f32_16x16x32_bf16 v[40:43], v[168:171], v[182:185], v[40:43]
	v_mfma_f32_16x16x32_bf16 v[32:35], v[160:163], v[190:193], v[32:35]
	v_mfma_f32_16x16x32_bf16 v[24:27], v[168:171], v[190:193], v[24:27]
	v_mfma_f32_16x16x32_bf16 v[16:19], v[160:163], v[198:201], v[16:19]
	v_mfma_f32_16x16x32_bf16 v[8:11], v[168:171], v[198:201], v[8:11]
	v_mfma_f32_16x16x32_bf16 v[4:7], v[160:163], v[220:223], v[4:7]
	v_mfma_f32_16x16x32_bf16 v[0:3], v[168:171], v[220:223], v[0:3]
	v_mfma_f32_16x16x32_bf16 v[50:53], v[164:167], v[186:189], v[50:53]
	v_mfma_f32_16x16x32_bf16 v[40:43], v[172:175], v[186:189], v[40:43]
	v_mfma_f32_16x16x32_bf16 v[32:35], v[164:167], v[194:197], v[32:35]
	v_mfma_f32_16x16x32_bf16 v[24:27], v[172:175], v[194:197], v[24:27]
	v_mfma_f32_16x16x32_bf16 v[16:19], v[164:167], v[216:219], v[16:19]
	v_mfma_f32_16x16x32_bf16 v[8:11], v[172:175], v[216:219], v[8:11]
	v_mfma_f32_16x16x32_bf16 v[4:7], v[164:167], v[224:227], v[4:7]
	v_mfma_f32_16x16x32_bf16 v[0:3], v[172:175], v[224:227], v[0:3]
	s_barrier
	s_add_i32 s6, 0, 0x18000
	v_add_u32_e32 v48, s6, v177
	s_add_i32 s26, 0, 0x1c000
	ds_read_b128 v[142:145], v48
	ds_read_b128 v[146:149], v48 offset:1024
	ds_read_b128 v[150:153], v48 offset:2048
	ds_read_b128 v[156:159], v48 offset:3072
	v_add_u32_e32 v48, s26, v177
	ds_read_b128 v[160:163], v48
	ds_read_b128 v[164:167], v48 offset:1024
	ds_read_b128 v[168:171], v48 offset:2048
	ds_read_b128 v[172:175], v48 offset:3072
	s_add_u32 s20, s60, 0x40000
	s_addc_u32 s21, s61, 0
	s_mov_b32 m0, s65
	v_lshl_add_u64 v[234:235], s[20:21], 0, v[136:137]
	ds_read_b128 v[182:185], v180 offset:32768
	ds_read_b128 v[186:189], v180 offset:33792
	ds_read_b128 v[190:193], v180 offset:34816
	ds_read_b128 v[194:197], v180 offset:35840
	ds_read_b128 v[198:201], v180 offset:36864
	ds_read_b128 v[216:219], v180 offset:37888
	ds_read_b128 v[220:223], v180 offset:38912
	ds_read_b128 v[224:227], v180 offset:39936
	global_load_lds_dwordx4 v[234:235], off
	v_lshl_add_u64 v[234:235], s[20:21], 0, v[132:133]
	s_mov_b32 m0, s66
	s_nop 0
	global_load_lds_dwordx4 v[234:235], off
	s_waitcnt vmcnt(8)
	s_waitcnt lgkmcnt(0)
	s_barrier
	v_mfma_f32_16x16x32_bf16 v[126:129], v[142:145], v[182:185], v[126:129]
	v_mfma_f32_16x16x32_bf16 v[122:125], v[150:153], v[182:185], v[122:125]
	v_mfma_f32_16x16x32_bf16 v[118:121], v[142:145], v[190:193], v[118:121]
	v_mfma_f32_16x16x32_bf16 v[110:113], v[150:153], v[190:193], v[110:113]
	v_mfma_f32_16x16x32_bf16 v[102:105], v[142:145], v[198:201], v[102:105]
	v_mfma_f32_16x16x32_bf16 v[94:97], v[150:153], v[198:201], v[94:97]
	v_mfma_f32_16x16x32_bf16 v[86:89], v[142:145], v[220:223], v[86:89]
	v_mfma_f32_16x16x32_bf16 v[78:81], v[150:153], v[220:223], v[78:81]
	v_mfma_f32_16x16x32_bf16 v[126:129], v[146:149], v[186:189], v[126:129]
	v_mfma_f32_16x16x32_bf16 v[122:125], v[156:159], v[186:189], v[122:125]
	v_mfma_f32_16x16x32_bf16 v[118:121], v[146:149], v[194:197], v[118:121]
	v_mfma_f32_16x16x32_bf16 v[110:113], v[156:159], v[194:197], v[110:113]
	v_mfma_f32_16x16x32_bf16 v[102:105], v[146:149], v[216:219], v[102:105]
	v_mfma_f32_16x16x32_bf16 v[94:97], v[156:159], v[216:219], v[94:97]
	v_mfma_f32_16x16x32_bf16 v[86:89], v[146:149], v[224:227], v[86:89]
	v_mfma_f32_16x16x32_bf16 v[78:81], v[156:159], v[224:227], v[78:81]
	v_mfma_f32_16x16x32_bf16 v[114:117], v[160:163], v[182:185], v[114:117]
	v_mfma_f32_16x16x32_bf16 v[106:109], v[168:171], v[182:185], v[106:109]
	v_mfma_f32_16x16x32_bf16 v[98:101], v[160:163], v[190:193], v[98:101]
	v_mfma_f32_16x16x32_bf16 v[90:93], v[168:171], v[190:193], v[90:93]
	v_mfma_f32_16x16x32_bf16 v[82:85], v[160:163], v[198:201], v[82:85]
	v_mfma_f32_16x16x32_bf16 v[74:77], v[168:171], v[198:201], v[74:77]
	v_mfma_f32_16x16x32_bf16 v[70:73], v[160:163], v[220:223], v[70:73]
	v_mfma_f32_16x16x32_bf16 v[66:69], v[168:171], v[220:223], v[66:69]
	v_mfma_f32_16x16x32_bf16 v[114:117], v[164:167], v[186:189], v[114:117]
	v_mfma_f32_16x16x32_bf16 v[106:109], v[172:175], v[186:189], v[106:109]
	v_mfma_f32_16x16x32_bf16 v[98:101], v[164:167], v[194:197], v[98:101]
	v_mfma_f32_16x16x32_bf16 v[90:93], v[172:175], v[194:197], v[90:93]
	v_mfma_f32_16x16x32_bf16 v[82:85], v[164:167], v[216:219], v[82:85]
	v_mfma_f32_16x16x32_bf16 v[74:77], v[172:175], v[216:219], v[74:77]
	v_mfma_f32_16x16x32_bf16 v[70:73], v[164:167], v[224:227], v[70:73]
	v_mfma_f32_16x16x32_bf16 v[66:69], v[172:175], v[224:227], v[66:69]
	s_barrier
	s_add_i32 s6, s6, s62
	v_lshl_add_u64 v[202:203], v[202:203], 0, s[30:31]
	s_mov_b32 m0, s6
	ds_read_b128 v[182:185], v180 offset:49152
	ds_read_b128 v[186:189], v180 offset:50176
	ds_read_b128 v[190:193], v180 offset:51200
	ds_read_b128 v[194:197], v180 offset:52224
	ds_read_b128 v[198:201], v180 offset:53248
	ds_read_b128 v[216:219], v180 offset:54272
	ds_read_b128 v[220:223], v180 offset:55296
	ds_read_b128 v[224:227], v180 offset:56320
	global_load_lds_dwordx4 v[202:203], off
	s_add_i32 m0, s6, 0x2000
	s_add_u32 s20, s58, 0x40080
	v_lshl_add_u64 v[202:203], v[228:229], 0, s[30:31]
	s_addc_u32 s21, s59, 0
	s_add_i32 s6, s26, s62
	global_load_lds_dwordx4 v[202:203], off
	v_lshl_add_u64 v[202:203], s[20:21], 0, v[134:135]
	s_mov_b32 m0, s6
	s_nop 0
	global_load_lds_dwordx4 v[202:203], off
	v_lshl_add_u64 v[202:203], s[20:21], 0, v[130:131]
	s_add_i32 m0, s6, 0x2000
	s_nop 0
	global_load_lds_dwordx4 v[202:203], off
	v_lshl_add_u64 v[202:203], v[230:231], 0, s[30:31]
	s_mov_b32 m0, s18
	s_nop 0
	global_load_lds_dwordx4 v[202:203], off
	v_lshl_add_u64 v[202:203], v[232:233], 0, s[30:31]
	s_mov_b32 m0, s24
	s_nop 0
	global_load_lds_dwordx4 v[202:203], off
	s_waitcnt vmcnt(8)
	s_waitcnt lgkmcnt(0)
	s_barrier
	v_mfma_f32_16x16x32_bf16 v[62:65], v[142:145], v[182:185], v[62:65]
	v_mfma_f32_16x16x32_bf16 v[58:61], v[150:153], v[182:185], v[58:61]
	v_mfma_f32_16x16x32_bf16 v[54:57], v[142:145], v[190:193], v[54:57]
	v_mfma_f32_16x16x32_bf16 v[44:47], v[150:153], v[190:193], v[44:47]
	v_mfma_f32_16x16x32_bf16 v[36:39], v[142:145], v[198:201], v[36:39]
	v_mfma_f32_16x16x32_bf16 v[28:31], v[150:153], v[198:201], v[28:31]
	v_mfma_f32_16x16x32_bf16 v[20:23], v[142:145], v[220:223], v[20:23]
	v_mfma_f32_16x16x32_bf16 v[12:15], v[150:153], v[220:223], v[12:15]
	v_mfma_f32_16x16x32_bf16 v[62:65], v[146:149], v[186:189], v[62:65]
	v_mfma_f32_16x16x32_bf16 v[58:61], v[156:159], v[186:189], v[58:61]
	v_mfma_f32_16x16x32_bf16 v[54:57], v[146:149], v[194:197], v[54:57]
	v_mfma_f32_16x16x32_bf16 v[44:47], v[156:159], v[194:197], v[44:47]
	v_mfma_f32_16x16x32_bf16 v[36:39], v[146:149], v[216:219], v[36:39]
	v_mfma_f32_16x16x32_bf16 v[28:31], v[156:159], v[216:219], v[28:31]
	v_mfma_f32_16x16x32_bf16 v[20:23], v[146:149], v[224:227], v[20:23]
	v_mfma_f32_16x16x32_bf16 v[12:15], v[156:159], v[224:227], v[12:15]
	v_mfma_f32_16x16x32_bf16 v[50:53], v[160:163], v[182:185], v[50:53]
	v_mfma_f32_16x16x32_bf16 v[40:43], v[168:171], v[182:185], v[40:43]
	v_mfma_f32_16x16x32_bf16 v[32:35], v[160:163], v[190:193], v[32:35]
	v_mfma_f32_16x16x32_bf16 v[24:27], v[168:171], v[190:193], v[24:27]
	v_mfma_f32_16x16x32_bf16 v[16:19], v[160:163], v[198:201], v[16:19]
	v_mfma_f32_16x16x32_bf16 v[8:11], v[168:171], v[198:201], v[8:11]
	v_mfma_f32_16x16x32_bf16 v[4:7], v[160:163], v[220:223], v[4:7]
	v_mfma_f32_16x16x32_bf16 v[0:3], v[168:171], v[220:223], v[0:3]
	v_mfma_f32_16x16x32_bf16 v[50:53], v[164:167], v[186:189], v[50:53]
	v_mfma_f32_16x16x32_bf16 v[40:43], v[172:175], v[186:189], v[40:43]
	v_mfma_f32_16x16x32_bf16 v[32:35], v[164:167], v[194:197], v[32:35]
	v_mfma_f32_16x16x32_bf16 v[24:27], v[172:175], v[194:197], v[24:27]
	v_mfma_f32_16x16x32_bf16 v[16:19], v[164:167], v[216:219], v[16:19]
	v_mfma_f32_16x16x32_bf16 v[8:11], v[172:175], v[216:219], v[8:11]
	v_mfma_f32_16x16x32_bf16 v[4:7], v[164:167], v[224:227], v[4:7]
	v_mfma_f32_16x16x32_bf16 v[0:3], v[172:175], v[224:227], v[0:3]
	s_barrier
	s_add_i32 s71, s71, 2
	s_add_u32 s56, s56, 0x100
	s_addc_u32 s57, s57, 0
	s_add_u32 s69, s69, 0x100
	s_addc_u32 s70, s70, 0
	s_cmp_gt_u32 s71, 13
	s_cbranch_scc0 .LBB0_690
	s_and_b64 vcc, exec, s[44:45]
	s_cbranch_vccz .LBB0_693
	s_barrier

.LBB0_789:
	s_cmp_eq_u32 s18, 2
	s_cselect_b64 vcc, -1, 0
	s_add_i32 s6, 0, 0x10000
	v_add_u32_e32 v48, s6, v170
	s_add_i32 s7, 0, 0x14000
	ds_read_b128 v[158:161], v48
	ds_read_b128 v[162:165], v48 offset:1024
	ds_read_b128 v[178:181], v48 offset:2048
	ds_read_b128 v[182:185], v48 offset:3072
	v_add_u32_e32 v48, s7, v170
	ds_read_b128 v[186:189], v48
	ds_read_b128 v[190:193], v48 offset:1024
	ds_read_b128 v[194:197], v48 offset:2048
	ds_read_b128 v[198:201], v48 offset:3072
	v_lshl_add_u64 v[152:153], v[150:151], 0, s[34:35]
	v_cndmask_b32_e32 v203, v153, v145, vcc
	v_cndmask_b32_e32 v202, v152, v144, vcc
	v_cndmask_b32_e32 v249, v149, v147, vcc
	v_cndmask_b32_e32 v248, v148, v146, vcc
	v_lshl_add_u64 v[250:251], v[150:151], 0, v[140:141]
	s_add_i32 m0, s9, 0xc000
	ds_read_b128 v[216:219], v174
	ds_read_b128 v[220:223], v174 offset:1024
	ds_read_b128 v[224:227], v174 offset:2048
	ds_read_b128 v[228:231], v174 offset:3072
	ds_read_b128 v[232:235], v174 offset:4096
	ds_read_b128 v[236:239], v174 offset:5120
	ds_read_b128 v[240:243], v174 offset:6144
	ds_read_b128 v[244:247], v174 offset:7168
	global_load_lds_dwordx4 v[250:251], off
	v_lshl_add_u64 v[150:151], v[150:151], 0, v[142:143]
	s_add_i32 m0, s9, 0xe000
	s_nop 0
	global_load_lds_dwordx4 v[150:151], off
	s_waitcnt vmcnt(8)
	s_waitcnt lgkmcnt(0)
	s_barrier
	v_mfma_f32_16x16x32_bf16 v[126:129], v[158:161], v[216:219], v[126:129]
	v_mfma_f32_16x16x32_bf16 v[122:125], v[178:181], v[216:219], v[122:125]
	v_mfma_f32_16x16x32_bf16 v[118:121], v[158:161], v[224:227], v[118:121]
	v_mfma_f32_16x16x32_bf16 v[114:117], v[178:181], v[224:227], v[114:117]
	v_mfma_f32_16x16x32_bf16 v[110:113], v[158:161], v[232:235], v[110:113]
	v_mfma_f32_16x16x32_bf16 v[106:109], v[178:181], v[232:235], v[106:109]
	v_mfma_f32_16x16x32_bf16 v[102:105], v[158:161], v[240:243], v[102:105]
	v_mfma_f32_16x16x32_bf16 v[98:101], v[178:181], v[240:243], v[98:101]
	v_mfma_f32_16x16x32_bf16 v[126:129], v[162:165], v[220:223], v[126:129]
	v_mfma_f32_16x16x32_bf16 v[122:125], v[182:185], v[220:223], v[122:125]
	v_mfma_f32_16x16x32_bf16 v[118:121], v[162:165], v[228:231], v[118:121]
	v_mfma_f32_16x16x32_bf16 v[114:117], v[182:185], v[228:231], v[114:117]
	v_mfma_f32_16x16x32_bf16 v[110:113], v[162:165], v[236:239], v[110:113]
	v_mfma_f32_16x16x32_bf16 v[106:109], v[182:185], v[236:239], v[106:109]
	v_mfma_f32_16x16x32_bf16 v[102:105], v[162:165], v[244:247], v[102:105]
	v_mfma_f32_16x16x32_bf16 v[98:101], v[182:185], v[244:247], v[98:101]
	v_mfma_f32_16x16x32_bf16 v[62:65], v[186:189], v[216:219], v[62:65]
	v_mfma_f32_16x16x32_bf16 v[58:61], v[194:197], v[216:219], v[58:61]
	v_mfma_f32_16x16x32_bf16 v[54:57], v[186:189], v[224:227], v[54:57]
	v_mfma_f32_16x16x32_bf16 v[50:53], v[194:197], v[224:227], v[50:53]
	v_mfma_f32_16x16x32_bf16 v[44:47], v[186:189], v[232:235], v[44:47]
	v_mfma_f32_16x16x32_bf16 v[40:43], v[194:197], v[232:235], v[40:43]
	v_mfma_f32_16x16x32_bf16 v[36:39], v[186:189], v[240:243], v[36:39]
	v_mfma_f32_16x16x32_bf16 v[32:35], v[194:197], v[240:243], v[32:35]
	v_mfma_f32_16x16x32_bf16 v[62:65], v[190:193], v[220:223], v[62:65]
	v_mfma_f32_16x16x32_bf16 v[58:61], v[198:201], v[220:223], v[58:61]
	v_mfma_f32_16x16x32_bf16 v[54:57], v[190:193], v[228:231], v[54:57]
	v_mfma_f32_16x16x32_bf16 v[50:53], v[198:201], v[228:231], v[50:53]
	v_mfma_f32_16x16x32_bf16 v[44:47], v[190:193], v[236:239], v[44:47]
	v_mfma_f32_16x16x32_bf16 v[40:43], v[198:201], v[236:239], v[40:43]
	v_mfma_f32_16x16x32_bf16 v[36:39], v[190:193], v[244:247], v[36:39]
	v_mfma_f32_16x16x32_bf16 v[32:35], v[198:201], v[244:247], v[32:35]
	s_barrier
	s_add_i32 s6, s6, s8
	v_lshl_add_u64 v[150:151], v[248:249], 0, v[134:135]
	s_mov_b32 m0, s6
	ds_read_b128 v[216:219], v174 offset:16384
	ds_read_b128 v[220:223], v174 offset:17408
	ds_read_b128 v[224:227], v174 offset:18432
	ds_read_b128 v[228:231], v174 offset:19456
	ds_read_b128 v[232:235], v174 offset:20480
	ds_read_b128 v[236:239], v174 offset:21504
	ds_read_b128 v[240:243], v174 offset:22528
	ds_read_b128 v[244:247], v174 offset:23552
	global_load_lds_dwordx4 v[150:151], off
	v_lshl_add_u64 v[250:251], v[248:249], 0, v[138:139]
	s_add_i32 m0, s6, 0x2000
	v_lshl_add_u64 v[252:253], v[248:249], 0, s[4:5]
	s_add_i32 s6, s7, s8
	global_load_lds_dwordx4 v[250:251], off
	v_lshl_add_u64 v[214:215], v[252:253], 0, v[134:135]
	s_mov_b32 m0, s6
	s_nop 0
	global_load_lds_dwordx4 v[214:215], off
	v_lshl_add_u64 v[214:215], v[252:253], 0, v[138:139]
	s_add_i32 m0, s6, 0x2000
	v_lshl_add_u64 v[252:253], v[202:203], 0, v[136:137]
	global_load_lds_dwordx4 v[214:215], off
	v_lshl_add_u64 v[214:215], v[202:203], 0, v[132:133]
	s_mov_b32 m0, s9
	s_nop 0
	global_load_lds_dwordx4 v[214:215], off
	s_mov_b32 m0, s24
	s_nop 0
	global_load_lds_dwordx4 v[252:253], off
	s_waitcnt vmcnt(8)
	s_waitcnt lgkmcnt(0)
	s_barrier
	v_mfma_f32_16x16x32_bf16 v[94:97], v[158:161], v[216:219], v[94:97]
	v_mfma_f32_16x16x32_bf16 v[90:93], v[178:181], v[216:219], v[90:93]
	v_mfma_f32_16x16x32_bf16 v[86:89], v[158:161], v[224:227], v[86:89]
	v_mfma_f32_16x16x32_bf16 v[82:85], v[178:181], v[224:227], v[82:85]
	v_mfma_f32_16x16x32_bf16 v[78:81], v[158:161], v[232:235], v[78:81]
	v_mfma_f32_16x16x32_bf16 v[74:77], v[178:181], v[232:235], v[74:77]
	v_mfma_f32_16x16x32_bf16 v[70:73], v[158:161], v[240:243], v[70:73]
	v_mfma_f32_16x16x32_bf16 v[66:69], v[178:181], v[240:243], v[66:69]
	v_mfma_f32_16x16x32_bf16 v[94:97], v[162:165], v[220:223], v[94:97]
	v_mfma_f32_16x16x32_bf16 v[90:93], v[182:185], v[220:223], v[90:93]
	v_mfma_f32_16x16x32_bf16 v[86:89], v[162:165], v[228:231], v[86:89]
	v_mfma_f32_16x16x32_bf16 v[82:85], v[182:185], v[228:231], v[82:85]
	v_mfma_f32_16x16x32_bf16 v[78:81], v[162:165], v[236:239], v[78:81]
	v_mfma_f32_16x16x32_bf16 v[74:77], v[182:185], v[236:239], v[74:77]
	v_mfma_f32_16x16x32_bf16 v[70:73], v[162:165], v[244:247], v[70:73]
	v_mfma_f32_16x16x32_bf16 v[66:69], v[182:185], v[244:247], v[66:69]
	v_mfma_f32_16x16x32_bf16 v[28:31], v[186:189], v[216:219], v[28:31]
	v_mfma_f32_16x16x32_bf16 v[24:27], v[194:197], v[216:219], v[24:27]
	v_mfma_f32_16x16x32_bf16 v[20:23], v[186:189], v[224:227], v[20:23]
	v_mfma_f32_16x16x32_bf16 v[16:19], v[194:197], v[224:227], v[16:19]
	v_mfma_f32_16x16x32_bf16 v[12:15], v[186:189], v[232:235], v[12:15]
	v_mfma_f32_16x16x32_bf16 v[8:11], v[194:197], v[232:235], v[8:11]
	v_mfma_f32_16x16x32_bf16 v[4:7], v[186:189], v[240:243], v[4:7]
	v_mfma_f32_16x16x32_bf16 v[0:3], v[194:197], v[240:243], v[0:3]
	v_mfma_f32_16x16x32_bf16 v[28:31], v[190:193], v[220:223], v[28:31]
	v_mfma_f32_16x16x32_bf16 v[24:27], v[198:201], v[220:223], v[24:27]
	v_mfma_f32_16x16x32_bf16 v[20:23], v[190:193], v[228:231], v[20:23]
	v_mfma_f32_16x16x32_bf16 v[16:19], v[198:201], v[228:231], v[16:19]
	v_mfma_f32_16x16x32_bf16 v[12:15], v[190:193], v[236:239], v[12:15]
	v_mfma_f32_16x16x32_bf16 v[8:11], v[198:201], v[236:239], v[8:11]
	v_mfma_f32_16x16x32_bf16 v[4:7], v[190:193], v[244:247], v[4:7]
	v_mfma_f32_16x16x32_bf16 v[0:3], v[198:201], v[244:247], v[0:3]
	s_barrier
	s_add_i32 s6, 0, 0x18000
	v_add_u32_e32 v48, s6, v170
	s_add_i32 s7, 0, 0x1c000
	ds_read_b128 v[158:161], v48
	ds_read_b128 v[162:165], v48 offset:1024
	ds_read_b128 v[178:181], v48 offset:2048
	ds_read_b128 v[182:185], v48 offset:3072
	v_add_u32_e32 v48, s7, v170
	ds_read_b128 v[186:189], v48
	ds_read_b128 v[190:193], v48 offset:1024
	ds_read_b128 v[194:197], v48 offset:2048
	ds_read_b128 v[198:201], v48 offset:3072
	v_lshl_add_u64 v[202:203], v[202:203], 0, s[10:11]
	s_mov_b32 m0, s86
	v_lshl_add_u64 v[212:213], v[202:203], 0, v[132:133]
	ds_read_b128 v[216:219], v174 offset:32768
	ds_read_b128 v[220:223], v174 offset:33792
	ds_read_b128 v[224:227], v174 offset:34816
	ds_read_b128 v[228:231], v174 offset:35840
	ds_read_b128 v[232:235], v174 offset:36864
	ds_read_b128 v[236:239], v174 offset:37888
	ds_read_b128 v[240:243], v174 offset:38912
	ds_read_b128 v[244:247], v174 offset:39936
	global_load_lds_dwordx4 v[212:213], off
	v_lshl_add_u64 v[202:203], v[202:203], 0, v[136:137]
	s_mov_b32 m0, s87
	s_nop 0
	global_load_lds_dwordx4 v[202:203], off
	s_waitcnt vmcnt(8)
	s_waitcnt lgkmcnt(0)
	s_barrier
	v_mfma_f32_16x16x32_bf16 v[126:129], v[158:161], v[216:219], v[126:129]
	v_mfma_f32_16x16x32_bf16 v[122:125], v[178:181], v[216:219], v[122:125]
	v_mfma_f32_16x16x32_bf16 v[118:121], v[158:161], v[224:227], v[118:121]
	v_mfma_f32_16x16x32_bf16 v[114:117], v[178:181], v[224:227], v[114:117]
	v_mfma_f32_16x16x32_bf16 v[110:113], v[158:161], v[232:235], v[110:113]
	v_mfma_f32_16x16x32_bf16 v[106:109], v[178:181], v[232:235], v[106:109]
	v_mfma_f32_16x16x32_bf16 v[102:105], v[158:161], v[240:243], v[102:105]
	v_mfma_f32_16x16x32_bf16 v[98:101], v[178:181], v[240:243], v[98:101]
	v_mfma_f32_16x16x32_bf16 v[126:129], v[162:165], v[220:223], v[126:129]
	v_mfma_f32_16x16x32_bf16 v[122:125], v[182:185], v[220:223], v[122:125]
	v_mfma_f32_16x16x32_bf16 v[118:121], v[162:165], v[228:231], v[118:121]
	v_mfma_f32_16x16x32_bf16 v[114:117], v[182:185], v[228:231], v[114:117]
	v_mfma_f32_16x16x32_bf16 v[110:113], v[162:165], v[236:239], v[110:113]
	v_mfma_f32_16x16x32_bf16 v[106:109], v[182:185], v[236:239], v[106:109]
	v_mfma_f32_16x16x32_bf16 v[102:105], v[162:165], v[244:247], v[102:105]
	v_mfma_f32_16x16x32_bf16 v[98:101], v[182:185], v[244:247], v[98:101]
	v_mfma_f32_16x16x32_bf16 v[62:65], v[186:189], v[216:219], v[62:65]
	v_mfma_f32_16x16x32_bf16 v[58:61], v[194:197], v[216:219], v[58:61]
	v_mfma_f32_16x16x32_bf16 v[54:57], v[186:189], v[224:227], v[54:57]
	v_mfma_f32_16x16x32_bf16 v[50:53], v[194:197], v[224:227], v[50:53]
	v_mfma_f32_16x16x32_bf16 v[44:47], v[186:189], v[232:235], v[44:47]
	v_mfma_f32_16x16x32_bf16 v[40:43], v[194:197], v[232:235], v[40:43]
	v_mfma_f32_16x16x32_bf16 v[36:39], v[186:189], v[240:243], v[36:39]
	v_mfma_f32_16x16x32_bf16 v[32:35], v[194:197], v[240:243], v[32:35]
	v_mfma_f32_16x16x32_bf16 v[62:65], v[190:193], v[220:223], v[62:65]
	v_mfma_f32_16x16x32_bf16 v[58:61], v[198:201], v[220:223], v[58:61]
	v_mfma_f32_16x16x32_bf16 v[54:57], v[190:193], v[228:231], v[54:57]
	v_mfma_f32_16x16x32_bf16 v[50:53], v[198:201], v[228:231], v[50:53]
	v_mfma_f32_16x16x32_bf16 v[44:47], v[190:193], v[236:239], v[44:47]
	v_mfma_f32_16x16x32_bf16 v[40:43], v[198:201], v[236:239], v[40:43]
	v_mfma_f32_16x16x32_bf16 v[36:39], v[190:193], v[244:247], v[36:39]
	v_mfma_f32_16x16x32_bf16 v[32:35], v[198:201], v[244:247], v[32:35]
	s_barrier
	s_add_i32 s6, s6, s8
	v_lshl_add_u64 v[150:151], v[150:151], 0, s[30:31]
	s_mov_b32 m0, s6
	ds_read_b128 v[216:219], v174 offset:49152
	ds_read_b128 v[220:223], v174 offset:50176
	ds_read_b128 v[224:227], v174 offset:51200
	ds_read_b128 v[228:231], v174 offset:52224
	ds_read_b128 v[232:235], v174 offset:53248
	ds_read_b128 v[236:239], v174 offset:54272
	ds_read_b128 v[240:243], v174 offset:55296
	ds_read_b128 v[244:247], v174 offset:56320
	global_load_lds_dwordx4 v[150:151], off
	v_lshl_add_u64 v[150:151], v[250:251], 0, s[30:31]
	s_add_i32 m0, s6, 0x2000
	s_add_i32 s6, s7, s8
	global_load_lds_dwordx4 v[150:151], off
	v_lshl_add_u64 v[150:151], v[248:249], 0, s[14:15]
	v_lshl_add_u64 v[202:203], v[150:151], 0, v[134:135]
	s_mov_b32 m0, s6
	v_lshl_add_u64 v[150:151], v[150:151], 0, v[138:139]
	global_load_lds_dwordx4 v[202:203], off
	s_add_i32 m0, s6, 0x2000
	s_nop 0
	global_load_lds_dwordx4 v[150:151], off
	v_lshl_add_u64 v[150:151], v[214:215], 0, s[30:31]
	s_mov_b32 m0, s89
	s_nop 0
	global_load_lds_dwordx4 v[150:151], off
	v_lshl_add_u64 v[150:151], v[252:253], 0, s[30:31]
	s_mov_b32 m0, s90
	s_nop 0
	global_load_lds_dwordx4 v[150:151], off
	s_waitcnt vmcnt(8)
	s_waitcnt lgkmcnt(0)
	s_barrier
	v_mfma_f32_16x16x32_bf16 v[94:97], v[158:161], v[216:219], v[94:97]
	v_mfma_f32_16x16x32_bf16 v[90:93], v[178:181], v[216:219], v[90:93]
	v_mfma_f32_16x16x32_bf16 v[86:89], v[158:161], v[224:227], v[86:89]
	v_mfma_f32_16x16x32_bf16 v[82:85], v[178:181], v[224:227], v[82:85]
	v_mfma_f32_16x16x32_bf16 v[78:81], v[158:161], v[232:235], v[78:81]
	v_mfma_f32_16x16x32_bf16 v[74:77], v[178:181], v[232:235], v[74:77]
	v_mfma_f32_16x16x32_bf16 v[70:73], v[158:161], v[240:243], v[70:73]
	v_mfma_f32_16x16x32_bf16 v[66:69], v[178:181], v[240:243], v[66:69]
	v_mfma_f32_16x16x32_bf16 v[94:97], v[162:165], v[220:223], v[94:97]
	v_mfma_f32_16x16x32_bf16 v[90:93], v[182:185], v[220:223], v[90:93]
	v_mfma_f32_16x16x32_bf16 v[86:89], v[162:165], v[228:231], v[86:89]
	v_mfma_f32_16x16x32_bf16 v[82:85], v[182:185], v[228:231], v[82:85]
	v_mfma_f32_16x16x32_bf16 v[78:81], v[162:165], v[236:239], v[78:81]
	v_mfma_f32_16x16x32_bf16 v[74:77], v[182:185], v[236:239], v[74:77]
	v_mfma_f32_16x16x32_bf16 v[70:73], v[162:165], v[244:247], v[70:73]
	v_mfma_f32_16x16x32_bf16 v[66:69], v[182:185], v[244:247], v[66:69]
	v_mfma_f32_16x16x32_bf16 v[28:31], v[186:189], v[216:219], v[28:31]
	v_mfma_f32_16x16x32_bf16 v[24:27], v[194:197], v[216:219], v[24:27]
	v_mfma_f32_16x16x32_bf16 v[20:23], v[186:189], v[224:227], v[20:23]
	v_mfma_f32_16x16x32_bf16 v[16:19], v[194:197], v[224:227], v[16:19]
	v_mfma_f32_16x16x32_bf16 v[12:15], v[186:189], v[232:235], v[12:15]
	v_mfma_f32_16x16x32_bf16 v[8:11], v[194:197], v[232:235], v[8:11]
	v_mfma_f32_16x16x32_bf16 v[4:7], v[186:189], v[240:243], v[4:7]
	v_mfma_f32_16x16x32_bf16 v[0:3], v[194:197], v[240:243], v[0:3]
	v_mfma_f32_16x16x32_bf16 v[28:31], v[190:193], v[220:223], v[28:31]
	v_mfma_f32_16x16x32_bf16 v[24:27], v[198:201], v[220:223], v[24:27]
	v_mfma_f32_16x16x32_bf16 v[20:23], v[190:193], v[228:231], v[20:23]
	v_mfma_f32_16x16x32_bf16 v[16:19], v[198:201], v[228:231], v[16:19]
	v_mfma_f32_16x16x32_bf16 v[12:15], v[190:193], v[236:239], v[12:15]
	v_mfma_f32_16x16x32_bf16 v[8:11], v[198:201], v[236:239], v[8:11]
	v_mfma_f32_16x16x32_bf16 v[4:7], v[190:193], v[244:247], v[4:7]
	v_mfma_f32_16x16x32_bf16 v[0:3], v[198:201], v[244:247], v[0:3]
	s_barrier
	s_add_i32 s18, s18, 2
	v_lshl_add_u64 v[148:149], v[148:149], 0, s[34:35]
	s_cmp_gt_u32 s18, 3
	v_mov_b64_e32 v[150:151], v[152:153]
	s_cbranch_scc0 .LBB0_789
	s_and_b64 vcc, exec, s[64:65]
	s_cbranch_vccz .LBB0_792
	s_barrier

.LBB0_1301:
	s_add_u32 s6, s56, 0xfffc0080
	s_addc_u32 s20, s57, -1
	s_add_i32 s21, 0, 0x10000
	s_cmp_eq_u32 s70, 12
	s_cselect_b32 s61, s18, s20
	s_cselect_b32 s60, s33, s6
	v_add_u32_e32 v48, s21, v183
	s_cselect_b32 s59, s45, s69
	s_cselect_b32 s58, s47, s53
	s_add_i32 s6, 0, 0x14000
	ds_read_b128 v[122:125], v48
	ds_read_b128 v[130:133], v48 offset:1024
	ds_read_b128 v[138:141], v48 offset:2048
	ds_read_b128 v[142:145], v48 offset:3072
	v_add_u32_e32 v48, s6, v183
	ds_read_b128 v[146:149], v48
	ds_read_b128 v[150:153], v48 offset:1024
	ds_read_b128 v[168:171], v48 offset:2048
	ds_read_b128 v[172:175], v48 offset:3072
	v_lshl_add_u64 v[180:181], s[56:57], 0, v[164:165]
	s_add_i32 m0, s55, 0xc000
	ds_read_b128 v[176:179], v185
	ds_read_b128 v[186:189], v185 offset:1024
	ds_read_b128 v[190:193], v185 offset:2048
	ds_read_b128 v[194:197], v185 offset:3072
	ds_read_b128 v[198:201], v185 offset:4096
	ds_read_b128 v[216:219], v185 offset:5120
	ds_read_b128 v[220:223], v185 offset:6144
	ds_read_b128 v[224:227], v185 offset:7168
	global_load_lds_dwordx4 v[180:181], off
	v_lshl_add_u64 v[180:181], s[56:57], 0, v[166:167]
	s_add_i32 m0, s55, 0xe000
	s_nop 0
	global_load_lds_dwordx4 v[180:181], off
	s_waitcnt vmcnt(8)
	s_waitcnt lgkmcnt(0)
	s_barrier
	v_mfma_f32_16x16x32_bf16 v[134:137], v[122:125], v[176:179], v[134:137]
	v_mfma_f32_16x16x32_bf16 v[126:129], v[138:141], v[176:179], v[126:129]
	v_mfma_f32_16x16x32_bf16 v[110:113], v[122:125], v[190:193], v[110:113]
	v_mfma_f32_16x16x32_bf16 v[106:109], v[138:141], v[190:193], v[106:109]
	v_mfma_f32_16x16x32_bf16 v[94:97], v[122:125], v[198:201], v[94:97]
	v_mfma_f32_16x16x32_bf16 v[90:93], v[138:141], v[198:201], v[90:93]
	v_mfma_f32_16x16x32_bf16 v[78:81], v[122:125], v[220:223], v[78:81]
	v_mfma_f32_16x16x32_bf16 v[74:77], v[138:141], v[220:223], v[74:77]
	v_mfma_f32_16x16x32_bf16 v[134:137], v[130:133], v[186:189], v[134:137]
	v_mfma_f32_16x16x32_bf16 v[126:129], v[142:145], v[186:189], v[126:129]
	v_mfma_f32_16x16x32_bf16 v[110:113], v[130:133], v[194:197], v[110:113]
	v_mfma_f32_16x16x32_bf16 v[106:109], v[142:145], v[194:197], v[106:109]
	v_mfma_f32_16x16x32_bf16 v[94:97], v[130:133], v[216:219], v[94:97]
	v_mfma_f32_16x16x32_bf16 v[90:93], v[142:145], v[216:219], v[90:93]
	v_mfma_f32_16x16x32_bf16 v[78:81], v[130:133], v[224:227], v[78:81]
	v_mfma_f32_16x16x32_bf16 v[74:77], v[142:145], v[224:227], v[74:77]
	v_mfma_f32_16x16x32_bf16 v[118:121], v[146:149], v[176:179], v[118:121]
	v_mfma_f32_16x16x32_bf16 v[114:117], v[168:171], v[176:179], v[114:117]
	v_mfma_f32_16x16x32_bf16 v[102:105], v[146:149], v[190:193], v[102:105]
	v_mfma_f32_16x16x32_bf16 v[98:101], v[168:171], v[190:193], v[98:101]
	v_mfma_f32_16x16x32_bf16 v[86:89], v[146:149], v[198:201], v[86:89]
	v_mfma_f32_16x16x32_bf16 v[82:85], v[168:171], v[198:201], v[82:85]
	v_mfma_f32_16x16x32_bf16 v[70:73], v[146:149], v[220:223], v[70:73]
	v_mfma_f32_16x16x32_bf16 v[66:69], v[168:171], v[220:223], v[66:69]
	v_mfma_f32_16x16x32_bf16 v[118:121], v[150:153], v[186:189], v[118:121]
	v_mfma_f32_16x16x32_bf16 v[114:117], v[172:175], v[186:189], v[114:117]
	v_mfma_f32_16x16x32_bf16 v[102:105], v[150:153], v[194:197], v[102:105]
	v_mfma_f32_16x16x32_bf16 v[98:101], v[172:175], v[194:197], v[98:101]
	v_mfma_f32_16x16x32_bf16 v[86:89], v[150:153], v[216:219], v[86:89]
	v_mfma_f32_16x16x32_bf16 v[82:85], v[172:175], v[216:219], v[82:85]
	v_mfma_f32_16x16x32_bf16 v[70:73], v[150:153], v[224:227], v[70:73]
	v_mfma_f32_16x16x32_bf16 v[66:69], v[172:175], v[224:227], v[66:69]
	s_barrier
	s_add_i32 s20, s21, s24
	v_lshl_add_u64 v[180:181], s[58:59], 0, v[158:159]
	s_mov_b32 m0, s20
	ds_read_b128 v[176:179], v185 offset:16384
	ds_read_b128 v[186:189], v185 offset:17408
	ds_read_b128 v[190:193], v185 offset:18432
	ds_read_b128 v[194:197], v185 offset:19456
	ds_read_b128 v[198:201], v185 offset:20480
	ds_read_b128 v[216:219], v185 offset:21504
	ds_read_b128 v[220:223], v185 offset:22528
	ds_read_b128 v[224:227], v185 offset:23552
	global_load_lds_dwordx4 v[180:181], off
	s_add_i32 m0, s20, 0x2000
	s_add_u32 s20, s58, 0x40000
	v_lshl_add_u64 v[202:203], s[58:59], 0, v[162:163]
	s_addc_u32 s21, s59, 0
	s_add_i32 s6, s6, s24
	global_load_lds_dwordx4 v[202:203], off
	v_lshl_add_u64 v[212:213], s[20:21], 0, v[158:159]
	s_mov_b32 m0, s6
	v_lshl_add_u64 v[214:215], s[60:61], 0, v[160:161]
	global_load_lds_dwordx4 v[212:213], off
	v_lshl_add_u64 v[212:213], s[20:21], 0, v[162:163]
	s_add_i32 m0, s6, 0x2000
	s_nop 0
	global_load_lds_dwordx4 v[212:213], off
	v_lshl_add_u64 v[212:213], s[60:61], 0, v[156:157]
	s_mov_b32 m0, s55
	s_nop 0
	global_load_lds_dwordx4 v[212:213], off
	s_mov_b32 m0, s62
	s_nop 0
	global_load_lds_dwordx4 v[214:215], off
	s_waitcnt vmcnt(8)
	s_waitcnt lgkmcnt(0)
	s_barrier
	v_mfma_f32_16x16x32_bf16 v[62:65], v[122:125], v[176:179], v[62:65]
	v_mfma_f32_16x16x32_bf16 v[58:61], v[138:141], v[176:179], v[58:61]
	v_mfma_f32_16x16x32_bf16 v[44:47], v[122:125], v[190:193], v[44:47]
	v_mfma_f32_16x16x32_bf16 v[40:43], v[138:141], v[190:193], v[40:43]
	v_mfma_f32_16x16x32_bf16 v[28:31], v[122:125], v[198:201], v[28:31]
	v_mfma_f32_16x16x32_bf16 v[24:27], v[138:141], v[198:201], v[24:27]
	v_mfma_f32_16x16x32_bf16 v[12:15], v[122:125], v[220:223], v[12:15]
	v_mfma_f32_16x16x32_bf16 v[8:11], v[138:141], v[220:223], v[8:11]
	v_mfma_f32_16x16x32_bf16 v[62:65], v[130:133], v[186:189], v[62:65]
	v_mfma_f32_16x16x32_bf16 v[58:61], v[142:145], v[186:189], v[58:61]
	v_mfma_f32_16x16x32_bf16 v[44:47], v[130:133], v[194:197], v[44:47]
	v_mfma_f32_16x16x32_bf16 v[40:43], v[142:145], v[194:197], v[40:43]
	v_mfma_f32_16x16x32_bf16 v[28:31], v[130:133], v[216:219], v[28:31]
	v_mfma_f32_16x16x32_bf16 v[24:27], v[142:145], v[216:219], v[24:27]
	v_mfma_f32_16x16x32_bf16 v[12:15], v[130:133], v[224:227], v[12:15]
	v_mfma_f32_16x16x32_bf16 v[8:11], v[142:145], v[224:227], v[8:11]
	v_mfma_f32_16x16x32_bf16 v[54:57], v[146:149], v[176:179], v[54:57]
	v_mfma_f32_16x16x32_bf16 v[50:53], v[168:171], v[176:179], v[50:53]
	v_mfma_f32_16x16x32_bf16 v[36:39], v[146:149], v[190:193], v[36:39]
	v_mfma_f32_16x16x32_bf16 v[32:35], v[168:171], v[190:193], v[32:35]
	v_mfma_f32_16x16x32_bf16 v[20:23], v[146:149], v[198:201], v[20:23]
	v_mfma_f32_16x16x32_bf16 v[16:19], v[168:171], v[198:201], v[16:19]
	v_mfma_f32_16x16x32_bf16 v[4:7], v[146:149], v[220:223], v[4:7]
	v_mfma_f32_16x16x32_bf16 v[0:3], v[168:171], v[220:223], v[0:3]
	v_mfma_f32_16x16x32_bf16 v[54:57], v[150:153], v[186:189], v[54:57]
	v_mfma_f32_16x16x32_bf16 v[50:53], v[172:175], v[186:189], v[50:53]
	v_mfma_f32_16x16x32_bf16 v[36:39], v[150:153], v[194:197], v[36:39]
	v_mfma_f32_16x16x32_bf16 v[32:35], v[172:175], v[194:197], v[32:35]
	v_mfma_f32_16x16x32_bf16 v[20:23], v[150:153], v[216:219], v[20:23]
	v_mfma_f32_16x16x32_bf16 v[16:19], v[172:175], v[216:219], v[16:19]
	v_mfma_f32_16x16x32_bf16 v[4:7], v[150:153], v[224:227], v[4:7]
	v_mfma_f32_16x16x32_bf16 v[0:3], v[172:175], v[224:227], v[0:3]
	s_barrier
	s_add_i32 s6, 0, 0x18000
	v_add_u32_e32 v48, s6, v183
	s_add_i32 s26, 0, 0x1c000
	ds_read_b128 v[122:125], v48
	ds_read_b128 v[130:133], v48 offset:1024
	ds_read_b128 v[138:141], v48 offset:2048
	ds_read_b128 v[142:145], v48 offset:3072
	v_add_u32_e32 v48, s26, v183
	ds_read_b128 v[146:149], v48
	ds_read_b128 v[150:153], v48 offset:1024
	ds_read_b128 v[168:171], v48 offset:2048
	ds_read_b128 v[172:175], v48 offset:3072
	s_add_u32 s20, s60, 0x40000
	s_addc_u32 s21, s61, 0
	s_mov_b32 m0, s63
	v_lshl_add_u64 v[228:229], s[20:21], 0, v[156:157]
	ds_read_b128 v[176:179], v185 offset:32768
	ds_read_b128 v[186:189], v185 offset:33792
	ds_read_b128 v[190:193], v185 offset:34816
	ds_read_b128 v[194:197], v185 offset:35840
	ds_read_b128 v[198:201], v185 offset:36864
	ds_read_b128 v[216:219], v185 offset:37888
	ds_read_b128 v[220:223], v185 offset:38912
	ds_read_b128 v[224:227], v185 offset:39936
	global_load_lds_dwordx4 v[228:229], off
	v_lshl_add_u64 v[228:229], s[20:21], 0, v[160:161]
	s_mov_b32 m0, s64
	s_nop 0
	global_load_lds_dwordx4 v[228:229], off
	s_waitcnt vmcnt(8)
	s_waitcnt lgkmcnt(0)
	s_barrier
	v_mfma_f32_16x16x32_bf16 v[134:137], v[122:125], v[176:179], v[134:137]
	v_mfma_f32_16x16x32_bf16 v[126:129], v[138:141], v[176:179], v[126:129]
	v_mfma_f32_16x16x32_bf16 v[110:113], v[122:125], v[190:193], v[110:113]
	v_mfma_f32_16x16x32_bf16 v[106:109], v[138:141], v[190:193], v[106:109]
	v_mfma_f32_16x16x32_bf16 v[94:97], v[122:125], v[198:201], v[94:97]
	v_mfma_f32_16x16x32_bf16 v[90:93], v[138:141], v[198:201], v[90:93]
	v_mfma_f32_16x16x32_bf16 v[78:81], v[122:125], v[220:223], v[78:81]
	v_mfma_f32_16x16x32_bf16 v[74:77], v[138:141], v[220:223], v[74:77]
	v_mfma_f32_16x16x32_bf16 v[134:137], v[130:133], v[186:189], v[134:137]
	v_mfma_f32_16x16x32_bf16 v[126:129], v[142:145], v[186:189], v[126:129]
	v_mfma_f32_16x16x32_bf16 v[110:113], v[130:133], v[194:197], v[110:113]
	v_mfma_f32_16x16x32_bf16 v[106:109], v[142:145], v[194:197], v[106:109]
	v_mfma_f32_16x16x32_bf16 v[94:97], v[130:133], v[216:219], v[94:97]
	v_mfma_f32_16x16x32_bf16 v[90:93], v[142:145], v[216:219], v[90:93]
	v_mfma_f32_16x16x32_bf16 v[78:81], v[130:133], v[224:227], v[78:81]
	v_mfma_f32_16x16x32_bf16 v[74:77], v[142:145], v[224:227], v[74:77]
	v_mfma_f32_16x16x32_bf16 v[118:121], v[146:149], v[176:179], v[118:121]
	v_mfma_f32_16x16x32_bf16 v[114:117], v[168:171], v[176:179], v[114:117]
	v_mfma_f32_16x16x32_bf16 v[102:105], v[146:149], v[190:193], v[102:105]
	v_mfma_f32_16x16x32_bf16 v[98:101], v[168:171], v[190:193], v[98:101]
	v_mfma_f32_16x16x32_bf16 v[86:89], v[146:149], v[198:201], v[86:89]
	v_mfma_f32_16x16x32_bf16 v[82:85], v[168:171], v[198:201], v[82:85]
	v_mfma_f32_16x16x32_bf16 v[70:73], v[146:149], v[220:223], v[70:73]
	v_mfma_f32_16x16x32_bf16 v[66:69], v[168:171], v[220:223], v[66:69]
	v_mfma_f32_16x16x32_bf16 v[118:121], v[150:153], v[186:189], v[118:121]
	v_mfma_f32_16x16x32_bf16 v[114:117], v[172:175], v[186:189], v[114:117]
	v_mfma_f32_16x16x32_bf16 v[102:105], v[150:153], v[194:197], v[102:105]
	v_mfma_f32_16x16x32_bf16 v[98:101], v[172:175], v[194:197], v[98:101]
	v_mfma_f32_16x16x32_bf16 v[86:89], v[150:153], v[216:219], v[86:89]
	v_mfma_f32_16x16x32_bf16 v[82:85], v[172:175], v[216:219], v[82:85]
	v_mfma_f32_16x16x32_bf16 v[70:73], v[150:153], v[224:227], v[70:73]
	v_mfma_f32_16x16x32_bf16 v[66:69], v[172:175], v[224:227], v[66:69]
	s_barrier
	s_add_i32 s6, s6, s24
	v_lshl_add_u64 v[180:181], v[180:181], 0, s[30:31]
	s_mov_b32 m0, s6
	ds_read_b128 v[176:179], v185 offset:49152
	ds_read_b128 v[186:189], v185 offset:50176
	ds_read_b128 v[190:193], v185 offset:51200
	ds_read_b128 v[194:197], v185 offset:52224
	ds_read_b128 v[198:201], v185 offset:53248
	ds_read_b128 v[216:219], v185 offset:54272
	ds_read_b128 v[220:223], v185 offset:55296
	ds_read_b128 v[224:227], v185 offset:56320
	global_load_lds_dwordx4 v[180:181], off
	s_add_i32 m0, s6, 0x2000
	s_add_u32 s20, s58, 0x40080
	v_lshl_add_u64 v[180:181], v[202:203], 0, s[30:31]
	s_addc_u32 s21, s59, 0
	s_add_i32 s6, s26, s24
	global_load_lds_dwordx4 v[180:181], off
	v_lshl_add_u64 v[180:181], s[20:21], 0, v[158:159]
	s_mov_b32 m0, s6
	s_nop 0
	global_load_lds_dwordx4 v[180:181], off
	v_lshl_add_u64 v[180:181], s[20:21], 0, v[162:163]
	s_add_i32 m0, s6, 0x2000
	s_nop 0
	global_load_lds_dwordx4 v[180:181], off
	v_lshl_add_u64 v[180:181], v[212:213], 0, s[30:31]
	s_mov_b32 m0, s65
	s_nop 0
	global_load_lds_dwordx4 v[180:181], off
	v_lshl_add_u64 v[180:181], v[214:215], 0, s[30:31]
	s_mov_b32 m0, s66
	s_nop 0
	global_load_lds_dwordx4 v[180:181], off
	s_waitcnt vmcnt(8)
	s_waitcnt lgkmcnt(0)
	s_barrier
	v_mfma_f32_16x16x32_bf16 v[62:65], v[122:125], v[176:179], v[62:65]
	v_mfma_f32_16x16x32_bf16 v[58:61], v[138:141], v[176:179], v[58:61]
	v_mfma_f32_16x16x32_bf16 v[44:47], v[122:125], v[190:193], v[44:47]
	v_mfma_f32_16x16x32_bf16 v[40:43], v[138:141], v[190:193], v[40:43]
	v_mfma_f32_16x16x32_bf16 v[28:31], v[122:125], v[198:201], v[28:31]
	v_mfma_f32_16x16x32_bf16 v[24:27], v[138:141], v[198:201], v[24:27]
	v_mfma_f32_16x16x32_bf16 v[12:15], v[122:125], v[220:223], v[12:15]
	v_mfma_f32_16x16x32_bf16 v[8:11], v[138:141], v[220:223], v[8:11]
	v_mfma_f32_16x16x32_bf16 v[62:65], v[130:133], v[186:189], v[62:65]
	v_mfma_f32_16x16x32_bf16 v[58:61], v[142:145], v[186:189], v[58:61]
	v_mfma_f32_16x16x32_bf16 v[44:47], v[130:133], v[194:197], v[44:47]
	v_mfma_f32_16x16x32_bf16 v[40:43], v[142:145], v[194:197], v[40:43]
	v_mfma_f32_16x16x32_bf16 v[28:31], v[130:133], v[216:219], v[28:31]
	v_mfma_f32_16x16x32_bf16 v[24:27], v[142:145], v[216:219], v[24:27]
	v_mfma_f32_16x16x32_bf16 v[12:15], v[130:133], v[224:227], v[12:15]
	v_mfma_f32_16x16x32_bf16 v[8:11], v[142:145], v[224:227], v[8:11]
	v_mfma_f32_16x16x32_bf16 v[54:57], v[146:149], v[176:179], v[54:57]
	v_mfma_f32_16x16x32_bf16 v[50:53], v[168:171], v[176:179], v[50:53]
	v_mfma_f32_16x16x32_bf16 v[36:39], v[146:149], v[190:193], v[36:39]
	v_mfma_f32_16x16x32_bf16 v[32:35], v[168:171], v[190:193], v[32:35]
	v_mfma_f32_16x16x32_bf16 v[20:23], v[146:149], v[198:201], v[20:23]
	v_mfma_f32_16x16x32_bf16 v[16:19], v[168:171], v[198:201], v[16:19]
	v_mfma_f32_16x16x32_bf16 v[4:7], v[146:149], v[220:223], v[4:7]
	v_mfma_f32_16x16x32_bf16 v[0:3], v[168:171], v[220:223], v[0:3]
	v_mfma_f32_16x16x32_bf16 v[54:57], v[150:153], v[186:189], v[54:57]
	v_mfma_f32_16x16x32_bf16 v[50:53], v[172:175], v[186:189], v[50:53]
	v_mfma_f32_16x16x32_bf16 v[36:39], v[150:153], v[194:197], v[36:39]
	v_mfma_f32_16x16x32_bf16 v[32:35], v[172:175], v[194:197], v[32:35]
	v_mfma_f32_16x16x32_bf16 v[20:23], v[150:153], v[216:219], v[20:23]
	v_mfma_f32_16x16x32_bf16 v[16:19], v[172:175], v[216:219], v[16:19]
	v_mfma_f32_16x16x32_bf16 v[4:7], v[150:153], v[224:227], v[4:7]
	v_mfma_f32_16x16x32_bf16 v[0:3], v[172:175], v[224:227], v[0:3]
	s_barrier
	s_add_i32 s70, s70, 2
	s_add_u32 s56, s56, 0x100
	s_addc_u32 s57, s57, 0
	s_add_u32 s53, s53, 0x100
	s_addc_u32 s69, s69, 0
	s_cmp_gt_u32 s70, 13
	s_cbranch_scc0 .LBB0_1301
	s_and_b64 vcc, exec, s[40:41]
	s_cbranch_vccz .LBB0_1304
	s_barrier

.LBB0_1411:
	s_add_u32 s6, s52, 0xfffc0080
	s_addc_u32 s20, s53, -1
	s_add_i32 s21, 0, 0x10000
	s_cmp_eq_u32 s67, 12
	s_cselect_b32 s57, s33, s20
	s_cselect_b32 s56, s39, s6
	v_add_u32_e32 v48, s21, v173
	s_cselect_b32 s55, s43, s66
	s_cselect_b32 s54, s45, s65
	s_add_i32 s6, 0, 0x14000
	ds_read_b128 v[138:141], v48
	ds_read_b128 v[142:145], v48 offset:1024
	ds_read_b128 v[146:149], v48 offset:2048
	ds_read_b128 v[150:153], v48 offset:3072
	v_add_u32_e32 v48, s6, v173
	ds_read_b128 v[156:159], v48
	ds_read_b128 v[160:163], v48 offset:1024
	ds_read_b128 v[164:167], v48 offset:2048
	ds_read_b128 v[168:171], v48 offset:3072
	v_lshl_add_u64 v[202:203], s[52:53], 0, v[134:135]
	s_add_i32 m0, s59, 0xc000
	ds_read_b128 v[178:181], v176
	ds_read_b128 v[182:185], v176 offset:1024
	ds_read_b128 v[186:189], v176 offset:2048
	ds_read_b128 v[190:193], v176 offset:3072
	ds_read_b128 v[194:197], v176 offset:4096
	ds_read_b128 v[198:201], v176 offset:5120
	ds_read_b128 v[216:219], v176 offset:6144
	ds_read_b128 v[220:223], v176 offset:7168
	global_load_lds_dwordx4 v[202:203], off
	v_lshl_add_u64 v[202:203], s[52:53], 0, v[136:137]
	s_add_i32 m0, s59, 0xe000
	s_nop 0
	global_load_lds_dwordx4 v[202:203], off
	s_waitcnt vmcnt(8)
	s_waitcnt lgkmcnt(0)
	s_barrier
	v_mfma_f32_16x16x32_bf16 v[126:129], v[138:141], v[178:181], v[126:129]
	v_mfma_f32_16x16x32_bf16 v[122:125], v[146:149], v[178:181], v[122:125]
	v_mfma_f32_16x16x32_bf16 v[110:113], v[138:141], v[186:189], v[110:113]
	v_mfma_f32_16x16x32_bf16 v[106:109], v[146:149], v[186:189], v[106:109]
	v_mfma_f32_16x16x32_bf16 v[94:97], v[138:141], v[194:197], v[94:97]
	v_mfma_f32_16x16x32_bf16 v[90:93], v[146:149], v[194:197], v[90:93]
	v_mfma_f32_16x16x32_bf16 v[78:81], v[138:141], v[216:219], v[78:81]
	v_mfma_f32_16x16x32_bf16 v[74:77], v[146:149], v[216:219], v[74:77]
	v_mfma_f32_16x16x32_bf16 v[126:129], v[142:145], v[182:185], v[126:129]
	v_mfma_f32_16x16x32_bf16 v[122:125], v[150:153], v[182:185], v[122:125]
	v_mfma_f32_16x16x32_bf16 v[110:113], v[142:145], v[190:193], v[110:113]
	v_mfma_f32_16x16x32_bf16 v[106:109], v[150:153], v[190:193], v[106:109]
	v_mfma_f32_16x16x32_bf16 v[94:97], v[142:145], v[198:201], v[94:97]
	v_mfma_f32_16x16x32_bf16 v[90:93], v[150:153], v[198:201], v[90:93]
	v_mfma_f32_16x16x32_bf16 v[78:81], v[142:145], v[220:223], v[78:81]
	v_mfma_f32_16x16x32_bf16 v[74:77], v[150:153], v[220:223], v[74:77]
	v_mfma_f32_16x16x32_bf16 v[118:121], v[156:159], v[178:181], v[118:121]
	v_mfma_f32_16x16x32_bf16 v[114:117], v[164:167], v[178:181], v[114:117]
	v_mfma_f32_16x16x32_bf16 v[102:105], v[156:159], v[186:189], v[102:105]
	v_mfma_f32_16x16x32_bf16 v[98:101], v[164:167], v[186:189], v[98:101]
	v_mfma_f32_16x16x32_bf16 v[86:89], v[156:159], v[194:197], v[86:89]
	v_mfma_f32_16x16x32_bf16 v[82:85], v[164:167], v[194:197], v[82:85]
	v_mfma_f32_16x16x32_bf16 v[70:73], v[156:159], v[216:219], v[70:73]
	v_mfma_f32_16x16x32_bf16 v[66:69], v[164:167], v[216:219], v[66:69]
	v_mfma_f32_16x16x32_bf16 v[118:121], v[160:163], v[182:185], v[118:121]
	v_mfma_f32_16x16x32_bf16 v[114:117], v[168:171], v[182:185], v[114:117]
	v_mfma_f32_16x16x32_bf16 v[102:105], v[160:163], v[190:193], v[102:105]
	v_mfma_f32_16x16x32_bf16 v[98:101], v[168:171], v[190:193], v[98:101]
	v_mfma_f32_16x16x32_bf16 v[86:89], v[160:163], v[198:201], v[86:89]
	v_mfma_f32_16x16x32_bf16 v[82:85], v[168:171], v[198:201], v[82:85]
	v_mfma_f32_16x16x32_bf16 v[70:73], v[160:163], v[220:223], v[70:73]
	v_mfma_f32_16x16x32_bf16 v[66:69], v[168:171], v[220:223], v[66:69]
	s_barrier
	s_add_i32 s20, s21, s58
	v_lshl_add_u64 v[202:203], s[54:55], 0, v[132:133]
	s_mov_b32 m0, s20
	ds_read_b128 v[178:181], v176 offset:16384
	ds_read_b128 v[182:185], v176 offset:17408
	ds_read_b128 v[186:189], v176 offset:18432
	ds_read_b128 v[190:193], v176 offset:19456
	ds_read_b128 v[194:197], v176 offset:20480
	ds_read_b128 v[198:201], v176 offset:21504
	ds_read_b128 v[216:219], v176 offset:22528
	ds_read_b128 v[220:223], v176 offset:23552
	global_load_lds_dwordx4 v[202:203], off
	s_add_i32 m0, s20, 0x2000
	s_add_u32 s20, s54, 0x40000
	v_lshl_add_u64 v[212:213], s[54:55], 0, v[130:131]
	s_addc_u32 s21, s55, 0
	s_add_i32 s6, s6, s58
	global_load_lds_dwordx4 v[212:213], off
	v_lshl_add_u64 v[214:215], s[20:21], 0, v[132:133]
	s_mov_b32 m0, s6
	v_lshl_add_u64 v[224:225], s[56:57], 0, v[130:131]
	global_load_lds_dwordx4 v[214:215], off
	v_lshl_add_u64 v[214:215], s[20:21], 0, v[130:131]
	s_add_i32 m0, s6, 0x2000
	s_nop 0
	global_load_lds_dwordx4 v[214:215], off
	v_lshl_add_u64 v[214:215], s[56:57], 0, v[132:133]
	s_mov_b32 m0, s59
	s_nop 0
	global_load_lds_dwordx4 v[214:215], off
	s_mov_b32 m0, s60
	s_nop 0
	global_load_lds_dwordx4 v[224:225], off
	s_waitcnt vmcnt(8)
	s_waitcnt lgkmcnt(0)
	s_barrier
	v_mfma_f32_16x16x32_bf16 v[62:65], v[138:141], v[178:181], v[62:65]
	v_mfma_f32_16x16x32_bf16 v[58:61], v[146:149], v[178:181], v[58:61]
	v_mfma_f32_16x16x32_bf16 v[44:47], v[138:141], v[186:189], v[44:47]
	v_mfma_f32_16x16x32_bf16 v[40:43], v[146:149], v[186:189], v[40:43]
	v_mfma_f32_16x16x32_bf16 v[28:31], v[138:141], v[194:197], v[28:31]
	v_mfma_f32_16x16x32_bf16 v[24:27], v[146:149], v[194:197], v[24:27]
	v_mfma_f32_16x16x32_bf16 v[12:15], v[138:141], v[216:219], v[12:15]
	v_mfma_f32_16x16x32_bf16 v[8:11], v[146:149], v[216:219], v[8:11]
	v_mfma_f32_16x16x32_bf16 v[62:65], v[142:145], v[182:185], v[62:65]
	v_mfma_f32_16x16x32_bf16 v[58:61], v[150:153], v[182:185], v[58:61]
	v_mfma_f32_16x16x32_bf16 v[44:47], v[142:145], v[190:193], v[44:47]
	v_mfma_f32_16x16x32_bf16 v[40:43], v[150:153], v[190:193], v[40:43]
	v_mfma_f32_16x16x32_bf16 v[28:31], v[142:145], v[198:201], v[28:31]
	v_mfma_f32_16x16x32_bf16 v[24:27], v[150:153], v[198:201], v[24:27]
	v_mfma_f32_16x16x32_bf16 v[12:15], v[142:145], v[220:223], v[12:15]
	v_mfma_f32_16x16x32_bf16 v[8:11], v[150:153], v[220:223], v[8:11]
	v_mfma_f32_16x16x32_bf16 v[54:57], v[156:159], v[178:181], v[54:57]
	v_mfma_f32_16x16x32_bf16 v[50:53], v[164:167], v[178:181], v[50:53]
	v_mfma_f32_16x16x32_bf16 v[36:39], v[156:159], v[186:189], v[36:39]
	v_mfma_f32_16x16x32_bf16 v[32:35], v[164:167], v[186:189], v[32:35]
	v_mfma_f32_16x16x32_bf16 v[20:23], v[156:159], v[194:197], v[20:23]
	v_mfma_f32_16x16x32_bf16 v[16:19], v[164:167], v[194:197], v[16:19]
	v_mfma_f32_16x16x32_bf16 v[4:7], v[156:159], v[216:219], v[4:7]
	v_mfma_f32_16x16x32_bf16 v[0:3], v[164:167], v[216:219], v[0:3]
	v_mfma_f32_16x16x32_bf16 v[54:57], v[160:163], v[182:185], v[54:57]
	v_mfma_f32_16x16x32_bf16 v[50:53], v[168:171], v[182:185], v[50:53]
	v_mfma_f32_16x16x32_bf16 v[36:39], v[160:163], v[190:193], v[36:39]
	v_mfma_f32_16x16x32_bf16 v[32:35], v[168:171], v[190:193], v[32:35]
	v_mfma_f32_16x16x32_bf16 v[20:23], v[160:163], v[198:201], v[20:23]
	v_mfma_f32_16x16x32_bf16 v[16:19], v[168:171], v[198:201], v[16:19]
	v_mfma_f32_16x16x32_bf16 v[4:7], v[160:163], v[220:223], v[4:7]
	v_mfma_f32_16x16x32_bf16 v[0:3], v[168:171], v[220:223], v[0:3]
	s_barrier
	s_add_i32 s6, 0, 0x18000
	v_add_u32_e32 v48, s6, v173
	s_add_i32 s26, 0, 0x1c000
	ds_read_b128 v[138:141], v48
	ds_read_b128 v[142:145], v48 offset:1024
	ds_read_b128 v[146:149], v48 offset:2048
	ds_read_b128 v[150:153], v48 offset:3072
	v_add_u32_e32 v48, s26, v173
	ds_read_b128 v[156:159], v48
	ds_read_b128 v[160:163], v48 offset:1024
	ds_read_b128 v[164:167], v48 offset:2048
	ds_read_b128 v[168:171], v48 offset:3072
	s_add_u32 s20, s56, 0x40000
	s_addc_u32 s21, s57, 0
	s_mov_b32 m0, s61
	v_lshl_add_u64 v[226:227], s[20:21], 0, v[132:133]
	ds_read_b128 v[178:181], v176 offset:32768
	ds_read_b128 v[182:185], v176 offset:33792
	ds_read_b128 v[186:189], v176 offset:34816
	ds_read_b128 v[190:193], v176 offset:35840
	ds_read_b128 v[194:197], v176 offset:36864
	ds_read_b128 v[198:201], v176 offset:37888
	ds_read_b128 v[216:219], v176 offset:38912
	ds_read_b128 v[220:223], v176 offset:39936
	global_load_lds_dwordx4 v[226:227], off
	v_lshl_add_u64 v[226:227], s[20:21], 0, v[130:131]
	s_mov_b32 m0, s62
	s_nop 0
	global_load_lds_dwordx4 v[226:227], off
	s_waitcnt vmcnt(8)
	s_waitcnt lgkmcnt(0)
	s_barrier
	v_mfma_f32_16x16x32_bf16 v[126:129], v[138:141], v[178:181], v[126:129]
	v_mfma_f32_16x16x32_bf16 v[122:125], v[146:149], v[178:181], v[122:125]
	v_mfma_f32_16x16x32_bf16 v[110:113], v[138:141], v[186:189], v[110:113]
	v_mfma_f32_16x16x32_bf16 v[106:109], v[146:149], v[186:189], v[106:109]
	v_mfma_f32_16x16x32_bf16 v[94:97], v[138:141], v[194:197], v[94:97]
	v_mfma_f32_16x16x32_bf16 v[90:93], v[146:149], v[194:197], v[90:93]
	v_mfma_f32_16x16x32_bf16 v[78:81], v[138:141], v[216:219], v[78:81]
	v_mfma_f32_16x16x32_bf16 v[74:77], v[146:149], v[216:219], v[74:77]
	v_mfma_f32_16x16x32_bf16 v[126:129], v[142:145], v[182:185], v[126:129]
	v_mfma_f32_16x16x32_bf16 v[122:125], v[150:153], v[182:185], v[122:125]
	v_mfma_f32_16x16x32_bf16 v[110:113], v[142:145], v[190:193], v[110:113]
	v_mfma_f32_16x16x32_bf16 v[106:109], v[150:153], v[190:193], v[106:109]
	v_mfma_f32_16x16x32_bf16 v[94:97], v[142:145], v[198:201], v[94:97]
	v_mfma_f32_16x16x32_bf16 v[90:93], v[150:153], v[198:201], v[90:93]
	v_mfma_f32_16x16x32_bf16 v[78:81], v[142:145], v[220:223], v[78:81]
	v_mfma_f32_16x16x32_bf16 v[74:77], v[150:153], v[220:223], v[74:77]
	v_mfma_f32_16x16x32_bf16 v[118:121], v[156:159], v[178:181], v[118:121]
	v_mfma_f32_16x16x32_bf16 v[114:117], v[164:167], v[178:181], v[114:117]
	v_mfma_f32_16x16x32_bf16 v[102:105], v[156:159], v[186:189], v[102:105]
	v_mfma_f32_16x16x32_bf16 v[98:101], v[164:167], v[186:189], v[98:101]
	v_mfma_f32_16x16x32_bf16 v[86:89], v[156:159], v[194:197], v[86:89]
	v_mfma_f32_16x16x32_bf16 v[82:85], v[164:167], v[194:197], v[82:85]
	v_mfma_f32_16x16x32_bf16 v[70:73], v[156:159], v[216:219], v[70:73]
	v_mfma_f32_16x16x32_bf16 v[66:69], v[164:167], v[216:219], v[66:69]
	v_mfma_f32_16x16x32_bf16 v[118:121], v[160:163], v[182:185], v[118:121]
	v_mfma_f32_16x16x32_bf16 v[114:117], v[168:171], v[182:185], v[114:117]
	v_mfma_f32_16x16x32_bf16 v[102:105], v[160:163], v[190:193], v[102:105]
	v_mfma_f32_16x16x32_bf16 v[98:101], v[168:171], v[190:193], v[98:101]
	v_mfma_f32_16x16x32_bf16 v[86:89], v[160:163], v[198:201], v[86:89]
	v_mfma_f32_16x16x32_bf16 v[82:85], v[168:171], v[198:201], v[82:85]
	v_mfma_f32_16x16x32_bf16 v[70:73], v[160:163], v[220:223], v[70:73]
	v_mfma_f32_16x16x32_bf16 v[66:69], v[168:171], v[220:223], v[66:69]
	s_barrier
	s_add_i32 s6, s6, s58
	v_lshl_add_u64 v[202:203], v[202:203], 0, s[30:31]
	s_mov_b32 m0, s6
	ds_read_b128 v[178:181], v176 offset:49152
	ds_read_b128 v[182:185], v176 offset:50176
	ds_read_b128 v[186:189], v176 offset:51200
	ds_read_b128 v[190:193], v176 offset:52224
	ds_read_b128 v[194:197], v176 offset:53248
	ds_read_b128 v[198:201], v176 offset:54272
	ds_read_b128 v[216:219], v176 offset:55296
	ds_read_b128 v[220:223], v176 offset:56320
	global_load_lds_dwordx4 v[202:203], off
	s_add_i32 m0, s6, 0x2000
	s_add_u32 s20, s54, 0x40080
	v_lshl_add_u64 v[202:203], v[212:213], 0, s[30:31]
	s_addc_u32 s21, s55, 0
	s_add_i32 s6, s26, s58
	global_load_lds_dwordx4 v[202:203], off
	v_lshl_add_u64 v[202:203], s[20:21], 0, v[132:133]
	s_mov_b32 m0, s6
	s_nop 0
	global_load_lds_dwordx4 v[202:203], off
	v_lshl_add_u64 v[202:203], s[20:21], 0, v[130:131]
	s_add_i32 m0, s6, 0x2000
	s_nop 0
	global_load_lds_dwordx4 v[202:203], off
	v_lshl_add_u64 v[202:203], v[214:215], 0, s[30:31]
	s_mov_b32 m0, s24
	s_nop 0
	global_load_lds_dwordx4 v[202:203], off
	v_lshl_add_u64 v[202:203], v[224:225], 0, s[30:31]
	s_mov_b32 m0, s63
	s_nop 0
	global_load_lds_dwordx4 v[202:203], off
	s_waitcnt vmcnt(8)
	s_waitcnt lgkmcnt(0)
	s_barrier
	v_mfma_f32_16x16x32_bf16 v[62:65], v[138:141], v[178:181], v[62:65]
	v_mfma_f32_16x16x32_bf16 v[58:61], v[146:149], v[178:181], v[58:61]
	v_mfma_f32_16x16x32_bf16 v[44:47], v[138:141], v[186:189], v[44:47]
	v_mfma_f32_16x16x32_bf16 v[40:43], v[146:149], v[186:189], v[40:43]
	v_mfma_f32_16x16x32_bf16 v[28:31], v[138:141], v[194:197], v[28:31]
	v_mfma_f32_16x16x32_bf16 v[24:27], v[146:149], v[194:197], v[24:27]
	v_mfma_f32_16x16x32_bf16 v[12:15], v[138:141], v[216:219], v[12:15]
	v_mfma_f32_16x16x32_bf16 v[8:11], v[146:149], v[216:219], v[8:11]
	v_mfma_f32_16x16x32_bf16 v[62:65], v[142:145], v[182:185], v[62:65]
	v_mfma_f32_16x16x32_bf16 v[58:61], v[150:153], v[182:185], v[58:61]
	v_mfma_f32_16x16x32_bf16 v[44:47], v[142:145], v[190:193], v[44:47]
	v_mfma_f32_16x16x32_bf16 v[40:43], v[150:153], v[190:193], v[40:43]
	v_mfma_f32_16x16x32_bf16 v[28:31], v[142:145], v[198:201], v[28:31]
	v_mfma_f32_16x16x32_bf16 v[24:27], v[150:153], v[198:201], v[24:27]
	v_mfma_f32_16x16x32_bf16 v[12:15], v[142:145], v[220:223], v[12:15]
	v_mfma_f32_16x16x32_bf16 v[8:11], v[150:153], v[220:223], v[8:11]
	v_mfma_f32_16x16x32_bf16 v[54:57], v[156:159], v[178:181], v[54:57]
	v_mfma_f32_16x16x32_bf16 v[50:53], v[164:167], v[178:181], v[50:53]
	v_mfma_f32_16x16x32_bf16 v[36:39], v[156:159], v[186:189], v[36:39]
	v_mfma_f32_16x16x32_bf16 v[32:35], v[164:167], v[186:189], v[32:35]
	v_mfma_f32_16x16x32_bf16 v[20:23], v[156:159], v[194:197], v[20:23]
	v_mfma_f32_16x16x32_bf16 v[16:19], v[164:167], v[194:197], v[16:19]
	v_mfma_f32_16x16x32_bf16 v[4:7], v[156:159], v[216:219], v[4:7]
	v_mfma_f32_16x16x32_bf16 v[0:3], v[164:167], v[216:219], v[0:3]
	v_mfma_f32_16x16x32_bf16 v[54:57], v[160:163], v[182:185], v[54:57]
	v_mfma_f32_16x16x32_bf16 v[50:53], v[168:171], v[182:185], v[50:53]
	v_mfma_f32_16x16x32_bf16 v[36:39], v[160:163], v[190:193], v[36:39]
	v_mfma_f32_16x16x32_bf16 v[32:35], v[168:171], v[190:193], v[32:35]
	v_mfma_f32_16x16x32_bf16 v[20:23], v[160:163], v[198:201], v[20:23]
	v_mfma_f32_16x16x32_bf16 v[16:19], v[168:171], v[198:201], v[16:19]
	v_mfma_f32_16x16x32_bf16 v[4:7], v[160:163], v[220:223], v[4:7]
	v_mfma_f32_16x16x32_bf16 v[0:3], v[168:171], v[220:223], v[0:3]
	s_barrier
	s_add_i32 s67, s67, 2
	s_add_u32 s52, s52, 0x100
	s_addc_u32 s53, s53, 0
	s_add_u32 s65, s65, 0x100
	s_addc_u32 s66, s66, 0
	s_cmp_gt_u32 s67, 13
	s_cbranch_scc0 .LBB0_1411
	s_and_b64 vcc, exec, s[40:41]
	s_cbranch_vccz .LBB0_1414
	s_barrier

.LBB0_1978:
	s_add_u32 s50, s48, 0x100
	s_addc_u32 s51, s49, 0
	s_add_i32 s6, 0, 0x10000
	s_cmp_eq_u32 s68, 40
	s_cselect_b32 s55, s45, s51
	s_cselect_b32 s54, s44, s50
	v_add_u32_e32 v48, s6, v183
	s_cselect_b32 s53, s47, s67
	s_cselect_b32 s52, s46, s66
	s_add_i32 s26, 0, 0x14000
	ds_read_b128 v[122:125], v48
	ds_read_b128 v[130:133], v48 offset:1024
	ds_read_b128 v[138:141], v48 offset:2048
	ds_read_b128 v[142:145], v48 offset:3072
	v_add_u32_e32 v48, s26, v183
	ds_read_b128 v[146:149], v48
	ds_read_b128 v[150:153], v48 offset:1024
	ds_read_b128 v[168:171], v48 offset:2048
	ds_read_b128 v[172:175], v48 offset:3072
	v_lshl_add_u64 v[180:181], s[48:49], 0, v[164:165]
	s_add_i32 m0, s56, 0xc000
	ds_read_b128 v[176:179], v185
	ds_read_b128 v[186:189], v185 offset:1024
	ds_read_b128 v[190:193], v185 offset:2048
	ds_read_b128 v[194:197], v185 offset:3072
	ds_read_b128 v[198:201], v185 offset:4096
	ds_read_b128 v[216:219], v185 offset:5120
	ds_read_b128 v[220:223], v185 offset:6144
	ds_read_b128 v[224:227], v185 offset:7168
	global_load_lds_dwordx4 v[180:181], off
	v_lshl_add_u64 v[180:181], s[48:49], 0, v[166:167]
	s_add_i32 m0, s56, 0xe000
	s_nop 0
	global_load_lds_dwordx4 v[180:181], off
	s_waitcnt vmcnt(8)
	s_waitcnt lgkmcnt(0)
	s_barrier
	v_mfma_f32_16x16x32_bf16 v[134:137], v[122:125], v[176:179], v[134:137]
	v_mfma_f32_16x16x32_bf16 v[126:129], v[138:141], v[176:179], v[126:129]
	v_mfma_f32_16x16x32_bf16 v[110:113], v[122:125], v[190:193], v[110:113]
	v_mfma_f32_16x16x32_bf16 v[106:109], v[138:141], v[190:193], v[106:109]
	v_mfma_f32_16x16x32_bf16 v[94:97], v[122:125], v[198:201], v[94:97]
	v_mfma_f32_16x16x32_bf16 v[90:93], v[138:141], v[198:201], v[90:93]
	v_mfma_f32_16x16x32_bf16 v[78:81], v[122:125], v[220:223], v[78:81]
	v_mfma_f32_16x16x32_bf16 v[74:77], v[138:141], v[220:223], v[74:77]
	v_mfma_f32_16x16x32_bf16 v[134:137], v[130:133], v[186:189], v[134:137]
	v_mfma_f32_16x16x32_bf16 v[126:129], v[142:145], v[186:189], v[126:129]
	v_mfma_f32_16x16x32_bf16 v[110:113], v[130:133], v[194:197], v[110:113]
	v_mfma_f32_16x16x32_bf16 v[106:109], v[142:145], v[194:197], v[106:109]
	v_mfma_f32_16x16x32_bf16 v[94:97], v[130:133], v[216:219], v[94:97]
	v_mfma_f32_16x16x32_bf16 v[90:93], v[142:145], v[216:219], v[90:93]
	v_mfma_f32_16x16x32_bf16 v[78:81], v[130:133], v[224:227], v[78:81]
	v_mfma_f32_16x16x32_bf16 v[74:77], v[142:145], v[224:227], v[74:77]
	v_mfma_f32_16x16x32_bf16 v[118:121], v[146:149], v[176:179], v[118:121]
	v_mfma_f32_16x16x32_bf16 v[114:117], v[168:171], v[176:179], v[114:117]
	v_mfma_f32_16x16x32_bf16 v[102:105], v[146:149], v[190:193], v[102:105]
	v_mfma_f32_16x16x32_bf16 v[98:101], v[168:171], v[190:193], v[98:101]
	v_mfma_f32_16x16x32_bf16 v[86:89], v[146:149], v[198:201], v[86:89]
	v_mfma_f32_16x16x32_bf16 v[82:85], v[168:171], v[198:201], v[82:85]
	v_mfma_f32_16x16x32_bf16 v[70:73], v[146:149], v[220:223], v[70:73]
	v_mfma_f32_16x16x32_bf16 v[66:69], v[168:171], v[220:223], v[66:69]
	v_mfma_f32_16x16x32_bf16 v[118:121], v[150:153], v[186:189], v[118:121]
	v_mfma_f32_16x16x32_bf16 v[114:117], v[172:175], v[186:189], v[114:117]
	v_mfma_f32_16x16x32_bf16 v[102:105], v[150:153], v[194:197], v[102:105]
	v_mfma_f32_16x16x32_bf16 v[98:101], v[172:175], v[194:197], v[98:101]
	v_mfma_f32_16x16x32_bf16 v[86:89], v[150:153], v[216:219], v[86:89]
	v_mfma_f32_16x16x32_bf16 v[82:85], v[172:175], v[216:219], v[82:85]
	v_mfma_f32_16x16x32_bf16 v[70:73], v[150:153], v[224:227], v[70:73]
	v_mfma_f32_16x16x32_bf16 v[66:69], v[172:175], v[224:227], v[66:69]
	s_barrier
	s_add_i32 s6, s6, s24
	v_lshl_add_u64 v[180:181], s[52:53], 0, v[158:159]
	s_mov_b32 m0, s6
	ds_read_b128 v[176:179], v185 offset:16384
	ds_read_b128 v[186:189], v185 offset:17408
	ds_read_b128 v[190:193], v185 offset:18432
	ds_read_b128 v[194:197], v185 offset:19456
	ds_read_b128 v[198:201], v185 offset:20480
	ds_read_b128 v[216:219], v185 offset:21504
	ds_read_b128 v[220:223], v185 offset:22528
	ds_read_b128 v[224:227], v185 offset:23552
	global_load_lds_dwordx4 v[180:181], off
	s_add_i32 m0, s6, 0x2000
	s_add_u32 s20, s52, 0xb0000
	v_lshl_add_u64 v[202:203], s[52:53], 0, v[162:163]
	s_addc_u32 s21, s53, 0
	s_add_i32 s6, s26, s24
	global_load_lds_dwordx4 v[202:203], off
	v_lshl_add_u64 v[212:213], s[20:21], 0, v[158:159]
	s_mov_b32 m0, s6
	v_lshl_add_u64 v[214:215], s[54:55], 0, v[160:161]
	global_load_lds_dwordx4 v[212:213], off
	v_lshl_add_u64 v[212:213], s[20:21], 0, v[162:163]
	s_add_i32 m0, s6, 0x2000
	s_nop 0
	global_load_lds_dwordx4 v[212:213], off
	v_lshl_add_u64 v[212:213], s[54:55], 0, v[156:157]
	s_mov_b32 m0, s56
	s_nop 0
	global_load_lds_dwordx4 v[212:213], off
	s_mov_b32 m0, s57
	s_nop 0
	global_load_lds_dwordx4 v[214:215], off
	s_waitcnt vmcnt(8)
	s_waitcnt lgkmcnt(0)
	s_barrier
	v_mfma_f32_16x16x32_bf16 v[62:65], v[122:125], v[176:179], v[62:65]
	v_mfma_f32_16x16x32_bf16 v[58:61], v[138:141], v[176:179], v[58:61]
	v_mfma_f32_16x16x32_bf16 v[44:47], v[122:125], v[190:193], v[44:47]
	v_mfma_f32_16x16x32_bf16 v[40:43], v[138:141], v[190:193], v[40:43]
	v_mfma_f32_16x16x32_bf16 v[28:31], v[122:125], v[198:201], v[28:31]
	v_mfma_f32_16x16x32_bf16 v[24:27], v[138:141], v[198:201], v[24:27]
	v_mfma_f32_16x16x32_bf16 v[12:15], v[122:125], v[220:223], v[12:15]
	v_mfma_f32_16x16x32_bf16 v[8:11], v[138:141], v[220:223], v[8:11]
	v_mfma_f32_16x16x32_bf16 v[62:65], v[130:133], v[186:189], v[62:65]
	v_mfma_f32_16x16x32_bf16 v[58:61], v[142:145], v[186:189], v[58:61]
	v_mfma_f32_16x16x32_bf16 v[44:47], v[130:133], v[194:197], v[44:47]
	v_mfma_f32_16x16x32_bf16 v[40:43], v[142:145], v[194:197], v[40:43]
	v_mfma_f32_16x16x32_bf16 v[28:31], v[130:133], v[216:219], v[28:31]
	v_mfma_f32_16x16x32_bf16 v[24:27], v[142:145], v[216:219], v[24:27]
	v_mfma_f32_16x16x32_bf16 v[12:15], v[130:133], v[224:227], v[12:15]
	v_mfma_f32_16x16x32_bf16 v[8:11], v[142:145], v[224:227], v[8:11]
	v_mfma_f32_16x16x32_bf16 v[54:57], v[146:149], v[176:179], v[54:57]
	v_mfma_f32_16x16x32_bf16 v[50:53], v[168:171], v[176:179], v[50:53]
	v_mfma_f32_16x16x32_bf16 v[36:39], v[146:149], v[190:193], v[36:39]
	v_mfma_f32_16x16x32_bf16 v[32:35], v[168:171], v[190:193], v[32:35]
	v_mfma_f32_16x16x32_bf16 v[20:23], v[146:149], v[198:201], v[20:23]
	v_mfma_f32_16x16x32_bf16 v[16:19], v[168:171], v[198:201], v[16:19]
	v_mfma_f32_16x16x32_bf16 v[4:7], v[146:149], v[220:223], v[4:7]
	v_mfma_f32_16x16x32_bf16 v[0:3], v[168:171], v[220:223], v[0:3]
	v_mfma_f32_16x16x32_bf16 v[54:57], v[150:153], v[186:189], v[54:57]
	v_mfma_f32_16x16x32_bf16 v[50:53], v[172:175], v[186:189], v[50:53]
	v_mfma_f32_16x16x32_bf16 v[36:39], v[150:153], v[194:197], v[36:39]
	v_mfma_f32_16x16x32_bf16 v[32:35], v[172:175], v[194:197], v[32:35]
	v_mfma_f32_16x16x32_bf16 v[20:23], v[150:153], v[216:219], v[20:23]
	v_mfma_f32_16x16x32_bf16 v[16:19], v[172:175], v[216:219], v[16:19]
	v_mfma_f32_16x16x32_bf16 v[4:7], v[150:153], v[224:227], v[4:7]
	v_mfma_f32_16x16x32_bf16 v[0:3], v[172:175], v[224:227], v[0:3]
	s_barrier
	s_add_i32 s6, 0, 0x18000
	v_add_u32_e32 v48, s6, v183
	s_add_i32 s26, 0, 0x1c000
	ds_read_b128 v[122:125], v48
	ds_read_b128 v[130:133], v48 offset:1024
	ds_read_b128 v[138:141], v48 offset:2048
	ds_read_b128 v[142:145], v48 offset:3072
	v_add_u32_e32 v48, s26, v183
	ds_read_b128 v[146:149], v48
	ds_read_b128 v[150:153], v48 offset:1024
	ds_read_b128 v[168:171], v48 offset:2048
	ds_read_b128 v[172:175], v48 offset:3072
	s_add_u32 s20, s54, 0xb0000
	s_addc_u32 s21, s55, 0
	s_mov_b32 m0, s58
	v_lshl_add_u64 v[228:229], s[20:21], 0, v[156:157]
	ds_read_b128 v[176:179], v185 offset:32768
	ds_read_b128 v[186:189], v185 offset:33792
	ds_read_b128 v[190:193], v185 offset:34816
	ds_read_b128 v[194:197], v185 offset:35840
	ds_read_b128 v[198:201], v185 offset:36864
	ds_read_b128 v[216:219], v185 offset:37888
	ds_read_b128 v[220:223], v185 offset:38912
	ds_read_b128 v[224:227], v185 offset:39936
	global_load_lds_dwordx4 v[228:229], off
	v_lshl_add_u64 v[228:229], s[20:21], 0, v[160:161]
	s_mov_b32 m0, s59
	s_nop 0
	global_load_lds_dwordx4 v[228:229], off
	s_waitcnt vmcnt(8)
	s_waitcnt lgkmcnt(0)
	s_barrier
	v_mfma_f32_16x16x32_bf16 v[134:137], v[122:125], v[176:179], v[134:137]
	v_mfma_f32_16x16x32_bf16 v[126:129], v[138:141], v[176:179], v[126:129]
	v_mfma_f32_16x16x32_bf16 v[110:113], v[122:125], v[190:193], v[110:113]
	v_mfma_f32_16x16x32_bf16 v[106:109], v[138:141], v[190:193], v[106:109]
	v_mfma_f32_16x16x32_bf16 v[94:97], v[122:125], v[198:201], v[94:97]
	v_mfma_f32_16x16x32_bf16 v[90:93], v[138:141], v[198:201], v[90:93]
	v_mfma_f32_16x16x32_bf16 v[78:81], v[122:125], v[220:223], v[78:81]
	v_mfma_f32_16x16x32_bf16 v[74:77], v[138:141], v[220:223], v[74:77]
	v_mfma_f32_16x16x32_bf16 v[134:137], v[130:133], v[186:189], v[134:137]
	v_mfma_f32_16x16x32_bf16 v[126:129], v[142:145], v[186:189], v[126:129]
	v_mfma_f32_16x16x32_bf16 v[110:113], v[130:133], v[194:197], v[110:113]
	v_mfma_f32_16x16x32_bf16 v[106:109], v[142:145], v[194:197], v[106:109]
	v_mfma_f32_16x16x32_bf16 v[94:97], v[130:133], v[216:219], v[94:97]
	v_mfma_f32_16x16x32_bf16 v[90:93], v[142:145], v[216:219], v[90:93]
	v_mfma_f32_16x16x32_bf16 v[78:81], v[130:133], v[224:227], v[78:81]
	v_mfma_f32_16x16x32_bf16 v[74:77], v[142:145], v[224:227], v[74:77]
	v_mfma_f32_16x16x32_bf16 v[118:121], v[146:149], v[176:179], v[118:121]
	v_mfma_f32_16x16x32_bf16 v[114:117], v[168:171], v[176:179], v[114:117]
	v_mfma_f32_16x16x32_bf16 v[102:105], v[146:149], v[190:193], v[102:105]
	v_mfma_f32_16x16x32_bf16 v[98:101], v[168:171], v[190:193], v[98:101]
	v_mfma_f32_16x16x32_bf16 v[86:89], v[146:149], v[198:201], v[86:89]
	v_mfma_f32_16x16x32_bf16 v[82:85], v[168:171], v[198:201], v[82:85]
	v_mfma_f32_16x16x32_bf16 v[70:73], v[146:149], v[220:223], v[70:73]
	v_mfma_f32_16x16x32_bf16 v[66:69], v[168:171], v[220:223], v[66:69]
	v_mfma_f32_16x16x32_bf16 v[118:121], v[150:153], v[186:189], v[118:121]
	v_mfma_f32_16x16x32_bf16 v[114:117], v[172:175], v[186:189], v[114:117]
	v_mfma_f32_16x16x32_bf16 v[102:105], v[150:153], v[194:197], v[102:105]
	v_mfma_f32_16x16x32_bf16 v[98:101], v[172:175], v[194:197], v[98:101]
	v_mfma_f32_16x16x32_bf16 v[86:89], v[150:153], v[216:219], v[86:89]
	v_mfma_f32_16x16x32_bf16 v[82:85], v[172:175], v[216:219], v[82:85]
	v_mfma_f32_16x16x32_bf16 v[70:73], v[150:153], v[224:227], v[70:73]
	v_mfma_f32_16x16x32_bf16 v[66:69], v[172:175], v[224:227], v[66:69]
	s_barrier
	s_add_i32 s6, s6, s24
	v_lshl_add_u64 v[180:181], v[180:181], 0, s[30:31]
	s_mov_b32 m0, s6
	ds_read_b128 v[176:179], v185 offset:49152
	ds_read_b128 v[186:189], v185 offset:50176
	ds_read_b128 v[190:193], v185 offset:51200
	ds_read_b128 v[194:197], v185 offset:52224
	ds_read_b128 v[198:201], v185 offset:53248
	ds_read_b128 v[216:219], v185 offset:54272
	ds_read_b128 v[220:223], v185 offset:55296
	ds_read_b128 v[224:227], v185 offset:56320
	global_load_lds_dwordx4 v[180:181], off
	s_add_i32 m0, s6, 0x2000
	s_add_u32 s20, s52, 0xb0080
	v_lshl_add_u64 v[180:181], v[202:203], 0, s[30:31]
	s_addc_u32 s21, s53, 0
	s_add_i32 s6, s26, s24
	global_load_lds_dwordx4 v[180:181], off
	v_lshl_add_u64 v[180:181], s[20:21], 0, v[158:159]
	s_mov_b32 m0, s6
	s_nop 0
	global_load_lds_dwordx4 v[180:181], off
	v_lshl_add_u64 v[180:181], s[20:21], 0, v[162:163]
	s_add_i32 m0, s6, 0x2000
	s_nop 0
	global_load_lds_dwordx4 v[180:181], off
	v_lshl_add_u64 v[180:181], v[212:213], 0, s[30:31]
	s_mov_b32 m0, s60
	s_nop 0
	global_load_lds_dwordx4 v[180:181], off
	v_lshl_add_u64 v[180:181], v[214:215], 0, s[30:31]
	s_mov_b32 m0, s61
	s_nop 0
	global_load_lds_dwordx4 v[180:181], off
	s_waitcnt vmcnt(8)
	s_waitcnt lgkmcnt(0)
	s_barrier
	v_mfma_f32_16x16x32_bf16 v[62:65], v[122:125], v[176:179], v[62:65]
	v_mfma_f32_16x16x32_bf16 v[58:61], v[138:141], v[176:179], v[58:61]
	v_mfma_f32_16x16x32_bf16 v[44:47], v[122:125], v[190:193], v[44:47]
	v_mfma_f32_16x16x32_bf16 v[40:43], v[138:141], v[190:193], v[40:43]
	v_mfma_f32_16x16x32_bf16 v[28:31], v[122:125], v[198:201], v[28:31]
	v_mfma_f32_16x16x32_bf16 v[24:27], v[138:141], v[198:201], v[24:27]
	v_mfma_f32_16x16x32_bf16 v[12:15], v[122:125], v[220:223], v[12:15]
	v_mfma_f32_16x16x32_bf16 v[8:11], v[138:141], v[220:223], v[8:11]
	v_mfma_f32_16x16x32_bf16 v[62:65], v[130:133], v[186:189], v[62:65]
	v_mfma_f32_16x16x32_bf16 v[58:61], v[142:145], v[186:189], v[58:61]
	v_mfma_f32_16x16x32_bf16 v[44:47], v[130:133], v[194:197], v[44:47]
	v_mfma_f32_16x16x32_bf16 v[40:43], v[142:145], v[194:197], v[40:43]
	v_mfma_f32_16x16x32_bf16 v[28:31], v[130:133], v[216:219], v[28:31]
	v_mfma_f32_16x16x32_bf16 v[24:27], v[142:145], v[216:219], v[24:27]
	v_mfma_f32_16x16x32_bf16 v[12:15], v[130:133], v[224:227], v[12:15]
	v_mfma_f32_16x16x32_bf16 v[8:11], v[142:145], v[224:227], v[8:11]
	v_mfma_f32_16x16x32_bf16 v[54:57], v[146:149], v[176:179], v[54:57]
	v_mfma_f32_16x16x32_bf16 v[50:53], v[168:171], v[176:179], v[50:53]
	v_mfma_f32_16x16x32_bf16 v[36:39], v[146:149], v[190:193], v[36:39]
	v_mfma_f32_16x16x32_bf16 v[32:35], v[168:171], v[190:193], v[32:35]
	v_mfma_f32_16x16x32_bf16 v[20:23], v[146:149], v[198:201], v[20:23]
	v_mfma_f32_16x16x32_bf16 v[16:19], v[168:171], v[198:201], v[16:19]
	v_mfma_f32_16x16x32_bf16 v[4:7], v[146:149], v[220:223], v[4:7]
	v_mfma_f32_16x16x32_bf16 v[0:3], v[168:171], v[220:223], v[0:3]
	v_mfma_f32_16x16x32_bf16 v[54:57], v[150:153], v[186:189], v[54:57]
	v_mfma_f32_16x16x32_bf16 v[50:53], v[172:175], v[186:189], v[50:53]
	v_mfma_f32_16x16x32_bf16 v[36:39], v[150:153], v[194:197], v[36:39]
	v_mfma_f32_16x16x32_bf16 v[32:35], v[172:175], v[194:197], v[32:35]
	v_mfma_f32_16x16x32_bf16 v[20:23], v[150:153], v[216:219], v[20:23]
	v_mfma_f32_16x16x32_bf16 v[16:19], v[172:175], v[216:219], v[16:19]
	v_mfma_f32_16x16x32_bf16 v[4:7], v[150:153], v[224:227], v[4:7]
	v_mfma_f32_16x16x32_bf16 v[0:3], v[172:175], v[224:227], v[0:3]
	s_barrier
	s_add_i32 s68, s68, 2
	s_add_u32 s66, s66, 0x100
	s_addc_u32 s67, s67, 0
	s_cmp_gt_u32 s68, 41
	s_mov_b64 s[48:49], s[50:51]
	s_cbranch_scc0 .LBB0_1978
	s_and_b64 vcc, exec, s[42:43]
	s_cbranch_vccz .LBB0_1981
	s_barrier
